# attention finalize gate loads nt
# speedup vs baseline: 1.0207x; 1.0207x over previous
; __device__ __forceinline__ void attn_unit_pp(int b, int h, int qb, int par, const bf16_t* __restrict__ QBp, const bf16_t* __restrict__ KBp, const bf16_t* __restrict__ VBp, ...
;     ...
;     unsigned gate16[64];
; #pragma unroll
;     for (int r = 0; r < 16; ++r)
; #pragma unroll
;       for (int d0 = 0; d0 < 4; ++d0) gate16[r * 4 + d0] = GATE_LD((r & 3) + 8 * (r >> 2), d0 * 32);
;     __syncthreads();
.LBB0_411:
	v_add_u32_e32 v36, 64, v34
	v_add_u32_e32 v37, 0x80, v34
	v_add_u32_e32 v38, 0xc0, v34
	v_add_u32_e32 v39, 0x1000, v34
	v_add_u32_e32 v40, 0x1040, v34
	v_add_u32_e32 v41, 0x1080, v34
	v_add_u32_e32 v42, 0x10c0, v34
	global_load_ushort v165, v34, s[20:21] nt
	global_load_ushort v163, v36, s[20:21] nt
	global_load_ushort v162, v37, s[20:21] nt
	global_load_ushort v159, v38, s[20:21] nt
	global_load_ushort v157, v39, s[20:21] nt
	global_load_ushort v154, v40, s[20:21] nt
	global_load_ushort v152, v41, s[20:21] nt
	global_load_ushort v149, v42, s[20:21] nt
	v_add_u32_e32 v36, 0x2000, v34
	v_add_u32_e32 v37, 0x2040, v34
	v_add_u32_e32 v38, 0x2080, v34
	v_add_u32_e32 v39, 0x20c0, v34
	v_add_u32_e32 v43, 0x30c0, v34
	v_add_u32_e32 v40, 0x3000, v34
	v_add_u32_e32 v41, 0x3040, v34
	v_add_u32_e32 v42, 0x3080, v34
	global_load_ushort v151, v36, s[20:21] nt
	global_load_ushort v148, v37, s[20:21] nt
	global_load_ushort v147, v38, s[20:21] nt
	global_load_ushort v143, v39, s[20:21] nt
	global_load_ushort v141, v40, s[20:21] nt
	global_load_ushort v139, v41, s[20:21] nt
	global_load_ushort v138, v42, s[20:21] nt
	global_load_ushort v134, v43, s[20:21] nt
	v_add_u32_e32 v36, 0x8000, v34
	v_add_u32_e32 v37, 0x8040, v34
	v_add_u32_e32 v38, 0x8080, v34
	v_add_u32_e32 v39, 0x80c0, v34
	v_add_u32_e32 v43, 0x90c0, v34
	v_add_u32_e32 v40, 0x9000, v34
	v_add_u32_e32 v41, 0x9040, v34
	v_add_u32_e32 v42, 0x9080, v34
	global_load_ushort v137, v36, s[20:21] nt
	global_load_ushort v133, v37, s[20:21] nt
	global_load_ushort v131, v38, s[20:21] nt
	global_load_ushort v130, v39, s[20:21] nt
	global_load_ushort v129, v40, s[20:21] nt
	global_load_ushort v126, v41, s[20:21] nt
	global_load_ushort v124, v42, s[20:21] nt
	global_load_ushort v122, v43, s[20:21] nt
	v_add_u32_e32 v36, 0xa000, v34
	v_add_u32_e32 v37, 0xa040, v34
	v_add_u32_e32 v38, 0xa080, v34
	v_add_u32_e32 v39, 0xa0c0, v34
	v_add_u32_e32 v43, 0xb0c0, v34
	v_add_u32_e32 v40, 0xb000, v34
	v_add_u32_e32 v41, 0xb040, v34
	v_add_u32_e32 v42, 0xb080, v34
	global_load_ushort v123, v36, s[20:21] nt
	global_load_ushort v121, v37, s[20:21] nt
	global_load_ushort v120, v38, s[20:21] nt
	global_load_ushort v117, v39, s[20:21] nt
	global_load_ushort v115, v40, s[20:21] nt
	global_load_ushort v114, v41, s[20:21] nt
	global_load_ushort v113, v42, s[20:21] nt
	global_load_ushort v109, v43, s[20:21] nt
	v_add_u32_e32 v36, 0x10000, v34
	v_add_u32_e32 v37, 0x10040, v34
	v_add_u32_e32 v38, 0x10080, v34
	v_add_u32_e32 v39, 0x100c0, v34
	v_add_u32_e32 v43, 0x110c0, v34
	v_add_u32_e32 v40, 0x11000, v34
	v_add_u32_e32 v41, 0x11040, v34
	v_add_u32_e32 v42, 0x11080, v34
	global_load_ushort v110, v36, s[20:21] nt
	global_load_ushort v108, v37, s[20:21] nt
	global_load_ushort v106, v38, s[20:21] nt
	global_load_ushort v105, v39, s[20:21] nt
	global_load_ushort v104, v40, s[20:21] nt
	global_load_ushort v102, v41, s[20:21] nt
	global_load_ushort v65, v42, s[20:21] nt
	global_load_ushort v63, v43, s[20:21] nt
	v_add_u32_e32 v36, 0x12000, v34
	v_add_u32_e32 v37, 0x12040, v34
	v_add_u32_e32 v38, 0x12080, v34
	v_add_u32_e32 v39, 0x120c0, v34
	v_add_u32_e32 v43, 0x130c0, v34
	v_add_u32_e32 v40, 0x13000, v34
	v_add_u32_e32 v41, 0x13040, v34
	v_add_u32_e32 v42, 0x13080, v34
	global_load_ushort v64, v36, s[20:21] nt
	global_load_ushort v62, v37, s[20:21] nt
	global_load_ushort v60, v38, s[20:21] nt
	global_load_ushort v59, v39, s[20:21] nt
	global_load_ushort v57, v40, s[20:21] nt
	global_load_ushort v56, v41, s[20:21] nt
	global_load_ushort v55, v42, s[20:21] nt
	global_load_ushort v53, v43, s[20:21] nt
	v_add_u32_e32 v36, 0x18000, v34
	v_add_u32_e32 v37, 0x18040, v34
	v_add_u32_e32 v38, 0x18080, v34
	v_add_u32_e32 v39, 0x180c0, v34
	v_add_u32_e32 v43, 0x190c0, v34
	v_add_u32_e32 v40, 0x19000, v34
	v_add_u32_e32 v41, 0x19040, v34
	v_add_u32_e32 v42, 0x19080, v34
	global_load_ushort v54, v36, s[20:21] nt
	global_load_ushort v52, v37, s[20:21] nt
	global_load_ushort v50, v38, s[20:21] nt
	global_load_ushort v49, v39, s[20:21] nt
	global_load_ushort v48, v40, s[20:21] nt
	global_load_ushort v47, v41, s[20:21] nt
	global_load_ushort v45, v42, s[20:21] nt
	s_nop 0
	global_load_ushort v43, v43, s[20:21] nt
	v_add_u32_e32 v36, 0x1a000, v34
	v_add_u32_e32 v37, 0x1a040, v34
	v_add_u32_e32 v38, 0x1a080, v34
	v_add_u32_e32 v39, 0x1a0c0, v34
	v_add_u32_e32 v46, 0x1b000, v34
	v_add_u32_e32 v51, 0x1b040, v34
	v_add_u32_e32 v58, 0x1b080, v34
	v_add_u32_e32 v61, 0x1b0c0, v34
	global_load_ushort v44, v36, s[20:21] nt
	global_load_ushort v42, v37, s[20:21] nt
	global_load_ushort v41, v38, s[20:21] nt
	global_load_ushort v40, v39, s[20:21] nt
	s_nop 0
	global_load_ushort v39, v46, s[20:21] nt
	global_load_ushort v38, v51, s[20:21] nt
	global_load_ushort v37, v58, s[20:21] nt
	global_load_ushort v36, v61, s[20:21] nt
	s_waitcnt vmcnt(63) expcnt(7) lgkmcnt(15)
	s_barrier
; __device__ __forceinline__ void attn_unit_pp(int b, int h, int qb, int par, const bf16_t* __restrict__ QBp, const bf16_t* __restrict__ KBp, const bf16_t* __restrict__ VBp, ...
;     ...
;     __syncthreads();
;     float ss[16];
; #pragma unroll
;     for (int r = 0; r < 16; ++r) ss[r] = 0.f;
; #pragma unroll
;     for (int d0 = 0; d0 < 4; ++d0)
; #pragma unroll
;       for (int r = 0; r < 16; ++r) { const float v = o[d0][r] - lam * xs[(d0 * 16 + r) * 64]; o[d0][r] = v; ss[r] += v * v; }
; #pragma unroll
;     for (int r = 0; r < 16; ++r) { float s = ss[r];
; #pragma unroll
;       for (int x = 1; x < 32; x <<= 1) s += __builtin_bit_cast(float, __builtin_amdgcn_ds_bpermute((lane ^ x) << 2, __builtin_bit_cast(int, s)));
;       ss[r] = 1.0f / sqrtf(s * (1.0f / 128.0f) + 1e-5f); }
	ds_read2st64_b32 v[118:119], v78 offset1:1
	ds_read2st64_b32 v[144:145], v78 offset0:2 offset1:3
	ds_read2st64_b32 v[160:161], v78 offset0:4 offset1:5
	ds_read2st64_b32 v[172:173], v78 offset0:6 offset1:7
	s_waitcnt lgkmcnt(3)
	v_fma_f32 v198, -v175, v118, v9
	v_fma_f32 v194, -v175, v119, v13
	s_waitcnt lgkmcnt(2)
	v_fma_f32 v190, -v175, v144, v17
	v_fma_f32 v186, -v175, v145, v32
	s_waitcnt lgkmcnt(0)
	v_fma_f32 v150, -v175, v172, v82
	ds_read2st64_b32 v[118:119], v78 offset0:8 offset1:9
	v_fma_f32 v140, -v175, v173, v22
	ds_read2st64_b32 v[144:145], v78 offset0:10 offset1:11
	ds_read2st64_b32 v[172:173], v78 offset0:12 offset1:13
	ds_read2st64_b32 v[184:185], v78 offset0:14 offset1:15
	v_fma_f32 v171, -v175, v160, v67
	v_fma_f32 v161, -v175, v161, v80
	s_waitcnt lgkmcnt(3)
	v_fma_f32 v132, -v175, v118, v86
	v_fma_f32 v125, -v175, v119, v88
	s_waitcnt lgkmcnt(2)
	v_fma_f32 v116, -v175, v144, v90
	v_fma_f32 v107, -v175, v145, v91
	s_waitcnt lgkmcnt(1)
	v_fma_f32 v101, -v175, v172, v93
	v_fma_f32 v58, -v175, v173, v96
	s_waitcnt lgkmcnt(0)
	v_fma_f32 v51, -v175, v184, v98
	ds_read2st64_b32 v[118:119], v78 offset0:16 offset1:17
	v_fma_f32 v46, -v175, v185, v100
	ds_read2st64_b32 v[144:145], v78 offset0:18 offset1:19
	ds_read2st64_b32 v[172:173], v78 offset0:20 offset1:21
	ds_read2st64_b32 v[184:185], v78 offset0:22 offset1:23
	s_waitcnt vmcnt(62)
	v_lshlrev_b32_e32 v163, 16, v163
	v_mul_f32_e32 v163, 0xbfb8aa3b, v163
	s_waitcnt lgkmcnt(3)
	v_fma_f32 v202, -v175, v118, v6
	v_fma_f32 v199, -v175, v119, v10
	s_waitcnt lgkmcnt(0)
	v_fma_f32 v167, -v175, v184, v70
	v_fma_f32 v158, -v175, v185, v83
	ds_read2st64_b32 v[118:119], v78 offset0:24 offset1:25
	ds_read2st64_b32 v[184:185], v78 offset0:26 offset1:27
	ds_read2st64_b32 v[188:189], v78 offset0:28 offset1:29
	ds_read2st64_b32 v[192:193], v78 offset0:30 offset1:31
	v_fma_f32 v187, -v175, v172, v33
	v_fma_f32 v172, -v175, v173, v69
	s_waitcnt lgkmcnt(2)
	v_fma_f32 v135, -v175, v184, v87
	v_fma_f32 v155, -v175, v118, v84
	v_fma_f32 v127, -v175, v185, v89
	s_waitcnt lgkmcnt(1)
	v_fma_f32 v118, -v175, v188, v92
	v_fma_f32 v111, -v175, v189, v94
	s_waitcnt lgkmcnt(0)
	v_fma_f32 v103, -v175, v192, v97
	v_fma_f32 v61, -v175, v193, v99
	ds_read2st64_b32 v[184:185], v78 offset0:32 offset1:33
	ds_read2st64_b32 v[188:189], v78 offset0:34 offset1:35
	ds_read2st64_b32 v[192:193], v78 offset0:36 offset1:37
	ds_read2st64_b32 v[226:227], v78 offset0:38 offset1:39
	v_mul_f32_e32 v142, v202, v202
	v_fmac_f32_e32 v142, v198, v198
	s_waitcnt lgkmcnt(2)
	v_fma_f32 v205, -v175, v188, v11
	v_fma_f32 v209, -v175, v184, v4
	s_waitcnt lgkmcnt(0)
	v_fma_f32 v188, -v175, v226, v81
	v_fma_f32 v184, -v175, v227, v71
	ds_read2st64_b32 v[226:227], v78 offset0:40 offset1:41
	ds_read2st64_b32 v[228:229], v78 offset0:42 offset1:43
	ds_read2st64_b32 v[230:231], v78 offset0:44 offset1:45
	ds_read2st64_b32 v[232:233], v78 offset0:46 offset1:47
	v_fmac_f32_e32 v142, v209, v209
	v_fma_f32 v195, -v175, v144, v14
	v_fma_f32 v191, -v175, v145, v18
	s_waitcnt lgkmcnt(3)
	v_fma_f32 v173, -v175, v226, v72
	v_fma_f32 v164, -v175, v227, v73
	ds_read2st64_b32 v[226:227], v78 offset0:48 offset1:49
	v_fma_f32 v145, -v175, v119, v85
	s_waitcnt lgkmcnt(3)
	v_fma_f32 v156, -v175, v228, v74
	v_fma_f32 v146, -v175, v229, v75
	s_waitcnt lgkmcnt(2)
	v_fma_f32 v136, -v175, v230, v76
	s_waitcnt lgkmcnt(0)
	v_fma_f32 v212, -v175, v226, v0
	v_fmac_f32_e32 v142, v212, v212
	v_fma_f32 v128, -v175, v231, v77
	v_fma_f32 v119, -v175, v232, v95
	v_fma_f32 v112, -v175, v233, v79
	ds_read2st64_b32 v[228:229], v78 offset0:50 offset1:51
	ds_read2st64_b32 v[230:231], v78 offset0:52 offset1:53
	ds_read2st64_b32 v[232:233], v78 offset0:54 offset1:55
	s_waitcnt lgkmcnt(0)
	s_nop 1
	v_add_f32_dpp v142, v142, v142 quad_perm:[1,0,3,2] row_mask:0xf bank_mask:0xf
	v_mul_f32_e32 v215, v199, v199
	v_fma_f32 v210, -v175, v227, v5
	ds_read2st64_b32 v[226:227], v78 offset0:56 offset1:57
	v_fmac_f32_e32 v215, v194, v194
	s_waitcnt lgkmcnt(0)
	s_nop 1
	v_add_f32_dpp v142, v142, v142 quad_perm:[2,3,0,1] row_mask:0xf bank_mask:0xf
	v_fma_f32 v207, -v175, v185, v7
	v_fma_f32 v208, -v175, v228, v8
	v_fma_f32 v206, -v175, v229, v12
	v_fma_f32 v204, -v175, v230, v16
	s_waitcnt lgkmcnt(0)
	s_nop 1
	v_add_f32_dpp v142, v142, v142 row_half_mirror row_mask:0xf bank_mask:0xf
	v_fma_f32 v203, -v175, v231, v20
	v_fma_f32 v200, -v175, v232, v21
	v_fma_f32 v196, -v175, v233, v23
	ds_read2st64_b32 v[228:229], v78 offset0:58 offset1:59
	ds_read2st64_b32 v[230:231], v78 offset0:60 offset1:61
	ds_read2st64_b32 v[232:233], v78 offset0:62 offset1:63
	s_waitcnt lgkmcnt(0)
	s_nop 1
	v_add_f32_dpp v142, v142, v142 row_mirror row_mask:0xf bank_mask:0xf
	v_fmac_f32_e32 v215, v207, v207
	v_fmac_f32_e32 v215, v210, v210
	s_waitcnt lgkmcnt(0)
	v_fma_f32 v170, -v175, v229, v27
	s_waitcnt lgkmcnt(0)
	v_mov_b32_e32 v144, v142
	s_nop 1
	v_permlane16_swap_b32_e32 v142, v144
	v_add_f32_e32 v142, v142, v144
	v_fmamk_f32 v142, v142, 0x3c000000, v177
	v_mul_f32_e32 v144, 0x4f800000, v142
	v_cmp_gt_f32_e32 vcc, s49, v142
	v_fma_f32 v197, -v175, v192, v19
	v_fma_f32 v192, -v175, v193, v66
	v_cndmask_b32_e32 v144, v142, v144, vcc
	v_fma_f32 v193, -v175, v226, v24
	v_sqrt_f32_e32 v226, v144
	v_fma_f32 v201, -v175, v189, v15
	v_fma_f32 v189, -v175, v227, v25
	s_waitcnt lgkmcnt(0)
	s_nop 1
	v_add_f32_dpp v215, v215, v215 quad_perm:[1,0,3,2] row_mask:0xf bank_mask:0xf
	v_add_u32_e32 v227, -1, v226
	v_fma_f32 v185, -v175, v228, v26
	v_fma_f32 v228, -v227, v226, v144
	v_cmp_ge_f32_e64 s[0:1], 0, v228
	v_add_u32_e32 v228, 1, v226
	v_mul_f32_e32 v216, v195, v195
	v_cndmask_b32_e64 v227, v226, v227, s[0:1]
	v_fma_f32 v226, -v228, v226, v144
	v_cmp_lt_f32_e64 s[0:1], 0, v226
	s_waitcnt lgkmcnt(0)
; __device__ __forceinline__ void attn_unit_pp(int b, int h, int qb, int par, const bf16_t* __restrict__ QBp, const bf16_t* __restrict__ KBp, const bf16_t* __restrict__ VBp, ...
;     ...
;       for (int r = 0; r < 16; ++r) { const float v = o[d0][r] - lam * xs[(d0 * 16 + r) * 64]; o[d0][r] = v; ss[r] += v * v; }
; #pragma unroll
;     for (int r = 0; r < 16; ++r) { float s = ss[r];
; #pragma unroll
;       for (int x = 1; x < 32; x <<= 1) s += __builtin_bit_cast(float, __builtin_amdgcn_ds_bpermute((lane ^ x) << 2, __builtin_bit_cast(int, s)));
;       ss[r] = 1.0f / sqrtf(s * (1.0f / 128.0f) + 1e-5f); }
	s_nop 1
	v_add_f32_dpp v215, v215, v215 quad_perm:[2,3,0,1] row_mask:0xf bank_mask:0xf
	v_fmac_f32_e32 v216, v190, v190
	v_cndmask_b32_e64 v226, v227, v228, s[0:1]
	v_mul_f32_e32 v227, 0x37800000, v226
	v_cndmask_b32_e32 v226, v226, v227, vcc
	v_cmp_class_f32_e32 vcc, v144, v176
	v_fmac_f32_e32 v216, v205, v205
	v_fmac_f32_e32 v216, v208, v208
	v_cndmask_b32_e32 v226, v226, v144, vcc
	s_waitcnt lgkmcnt(0)
	s_nop 1
	v_add_f32_dpp v215, v215, v215 row_half_mirror row_mask:0xf bank_mask:0xf
	v_div_scale_f32 v228, s[0:1], v226, v226, 1.0
	v_rcp_f32_e32 v229, v228
	v_fma_f32 v160, -v175, v230, v28
	s_waitcnt lgkmcnt(0)
	s_nop 1
	v_add_f32_dpp v215, v215, v215 row_mirror row_mask:0xf bank_mask:0xf
	v_fma_f32 v144, -v175, v233, v31
	v_fma_f32 v230, -v228, v229, 1.0
	v_fmac_f32_e32 v229, v230, v229
	s_waitcnt lgkmcnt(0)
	v_mov_b32_e32 v227, v215
	s_nop 1
	v_permlane16_swap_b32_e32 v215, v227
	v_add_f32_e32 v215, v215, v227
	v_fmamk_f32 v215, v215, 0x3c000000, v177
	v_mul_f32_e32 v227, 0x4f800000, v215
	v_cmp_gt_f32_e64 s[0:1], s49, v215
	v_div_scale_f32 v230, vcc, 1.0, v226, 1.0
	s_nop 0
	v_cndmask_b32_e64 v215, v215, v227, s[0:1]
	v_sqrt_f32_e32 v227, v215
	v_fma_f32 v153, -v175, v231, v29
	v_mul_f32_e32 v231, v230, v229
	v_fma_f32 v142, -v175, v232, v30
	v_fma_f32 v232, -v228, v231, v230
	v_fmac_f32_e32 v231, v232, v229
	v_fma_f32 v228, -v228, v231, v230
	v_add_u32_e32 v230, -1, v227
	s_waitcnt lgkmcnt(0)
	s_nop 1
	v_add_f32_dpp v216, v216, v216 quad_perm:[1,0,3,2] row_mask:0xf bank_mask:0xf
	v_fma_f32 v232, -v230, v227, v215
	v_cmp_ge_f32_e64 s[2:3], 0, v232
	v_add_u32_e32 v232, 1, v227
	v_mul_f32_e32 v218, v191, v191
	v_cndmask_b32_e64 v230, v227, v230, s[2:3]
	v_fma_f32 v227, -v232, v227, v215
	v_cmp_lt_f32_e64 s[2:3], 0, v227
	s_waitcnt lgkmcnt(0)
	s_nop 1
	v_add_f32_dpp v216, v216, v216 quad_perm:[2,3,0,1] row_mask:0xf bank_mask:0xf
	v_fmac_f32_e32 v218, v186, v186
	v_cndmask_b32_e64 v227, v230, v232, s[2:3]
	v_mul_f32_e32 v230, 0x37800000, v227
	v_cndmask_b32_e64 v227, v227, v230, s[0:1]
	v_cmp_class_f32_e64 s[0:1], v215, v176
	v_fmac_f32_e32 v218, v201, v201
	v_fmac_f32_e32 v218, v206, v206
	v_cndmask_b32_e64 v227, v227, v215, s[0:1]
	s_waitcnt lgkmcnt(0)
	s_nop 1
	v_add_f32_dpp v216, v216, v216 row_half_mirror row_mask:0xf bank_mask:0xf
	v_div_scale_f32 v232, s[0:1], v227, v227, 1.0
	v_rcp_f32_e32 v233, v232
	v_div_fmas_f32 v215, v228, v229, v231
	s_waitcnt lgkmcnt(0)
	s_nop 1
	v_add_f32_dpp v216, v216, v216 row_mirror row_mask:0xf bank_mask:0xf
	v_div_fixup_f32 v215, v215, v226, 1.0
	v_fma_f32 v226, -v232, v233, 1.0
	v_fmac_f32_e32 v233, v226, v233
	v_div_scale_f32 v226, vcc, 1.0, v227, 1.0
	v_mul_f32_e32 v229, v226, v233
	s_waitcnt lgkmcnt(0)
	v_mov_b32_e32 v228, v216
	s_nop 1
	v_permlane16_swap_b32_e32 v216, v228
	v_add_f32_e32 v216, v216, v228
	v_fmamk_f32 v216, v216, 0x3c000000, v177
	v_fma_f32 v230, -v232, v229, v226
	v_mul_f32_e32 v228, 0x4f800000, v216
	v_cmp_gt_f32_e64 s[0:1], s49, v216
	v_fmac_f32_e32 v229, v230, v233
	v_fma_f32 v226, -v232, v229, v226
	v_cndmask_b32_e64 v216, v216, v228, s[0:1]
	v_sqrt_f32_e32 v228, v216
	v_mul_f32_e32 v234, v187, v187
	v_fmac_f32_e32 v234, v171, v171
	v_fmac_f32_e32 v234, v197, v197
	v_add_u32_e32 v230, -1, v228
	s_waitcnt lgkmcnt(0)
	s_nop 1
	v_add_f32_dpp v218, v218, v218 quad_perm:[1,0,3,2] row_mask:0xf bank_mask:0xf
	v_fma_f32 v231, -v230, v228, v216
	v_cmp_ge_f32_e64 s[2:3], 0, v231
	v_add_u32_e32 v231, 1, v228
	v_fmac_f32_e32 v234, v204, v204
	v_cndmask_b32_e64 v230, v228, v230, s[2:3]
	v_fma_f32 v228, -v231, v228, v216
	v_cmp_lt_f32_e64 s[2:3], 0, v228
	s_waitcnt lgkmcnt(0)
	s_nop 1
	v_add_f32_dpp v218, v218, v218 quad_perm:[2,3,0,1] row_mask:0xf bank_mask:0xf
	v_mul_f32_e32 v219, v172, v172
	v_cndmask_b32_e64 v228, v230, v231, s[2:3]
	v_mul_f32_e32 v230, 0x37800000, v228
	v_cndmask_b32_e64 v228, v228, v230, s[0:1]
	v_cmp_class_f32_e64 s[0:1], v216, v176
	v_fmac_f32_e32 v219, v161, v161
	v_fmac_f32_e32 v219, v192, v192
	v_cndmask_b32_e64 v228, v228, v216, s[0:1]
	s_waitcnt lgkmcnt(0)
	s_nop 1
	v_add_f32_dpp v218, v218, v218 row_half_mirror row_mask:0xf bank_mask:0xf
	v_div_fmas_f32 v216, v226, v233, v229
	v_div_fixup_f32 v216, v216, v227, 1.0
	v_div_scale_f32 v231, s[0:1], v228, v228, 1.0
	s_waitcnt lgkmcnt(0)
	s_nop 1
	v_add_f32_dpp v218, v218, v218 row_mirror row_mask:0xf bank_mask:0xf
	v_rcp_f32_e32 v232, v231
	v_fmac_f32_e32 v219, v203, v203
	v_mul_f32_e32 v221, v167, v167
	s_waitcnt lgkmcnt(0)
	v_mov_b32_e32 v227, v218
	s_nop 1
	v_permlane16_swap_b32_e32 v218, v227
	v_add_f32_e32 v218, v218, v227
	v_fmamk_f32 v218, v218, 0x3c000000, v177
	v_mul_f32_e32 v227, 0x4f800000, v218
	v_cmp_gt_f32_e64 s[0:1], s49, v218
	v_fma_f32 v226, -v231, v232, 1.0
	v_fmac_f32_e32 v232, v226, v232
	v_cndmask_b32_e64 v218, v218, v227, s[0:1]
	v_sqrt_f32_e32 v227, v218
	v_div_scale_f32 v226, vcc, 1.0, v228, 1.0
	v_mul_f32_e32 v229, v226, v232
	v_fma_f32 v230, -v231, v229, v226
	v_fmac_f32_e32 v229, v230, v232
	v_add_u32_e32 v230, -1, v227
	v_fma_f32 v226, -v231, v229, v226
	v_fma_f32 v231, -v230, v227, v218
	s_waitcnt lgkmcnt(0)
	s_nop 1
	v_add_f32_dpp v233, v234, v234 quad_perm:[1,0,3,2] row_mask:0xf bank_mask:0xf
	v_cmp_ge_f32_e64 s[2:3], 0, v231
	v_add_u32_e32 v231, 1, v227
	v_cndmask_b32_e64 v230, v227, v230, s[2:3]
	v_fma_f32 v227, -v231, v227, v218
	v_cmp_lt_f32_e64 s[2:3], 0, v227
	v_fmac_f32_e32 v221, v150, v150
	v_fmac_f32_e32 v221, v188, v188
	v_cndmask_b32_e64 v227, v230, v231, s[2:3]
	v_mul_f32_e32 v230, 0x37800000, v227
	v_cndmask_b32_e64 v227, v227, v230, s[0:1]
	s_waitcnt lgkmcnt(0)
; __device__ __forceinline__ void attn_unit_pp(int b, int h, int qb, int par, const bf16_t* __restrict__ QBp, const bf16_t* __restrict__ KBp, const bf16_t* __restrict__ VBp, ...
;     ...
;       for (int r = 0; r < 16; ++r) { const float v = o[d0][r] - lam * xs[(d0 * 16 + r) * 64]; o[d0][r] = v; ss[r] += v * v; }
; #pragma unroll
;     for (int r = 0; r < 16; ++r) { float s = ss[r];
; #pragma unroll
;       for (int x = 1; x < 32; x <<= 1) s += __builtin_bit_cast(float, __builtin_amdgcn_ds_bpermute((lane ^ x) << 2, __builtin_bit_cast(int, s)));
;       ss[r] = 1.0f / sqrtf(s * (1.0f / 128.0f) + 1e-5f); }
	s_nop 1
	v_add_f32_dpp v230, v233, v233 quad_perm:[2,3,0,1] row_mask:0xf bank_mask:0xf
	v_cmp_class_f32_e64 s[0:1], v218, v176
	v_fmac_f32_e32 v221, v200, v200
	v_mul_f32_e32 v222, v158, v158
	v_cndmask_b32_e64 v227, v227, v218, s[0:1]
	s_waitcnt lgkmcnt(0)
	s_nop 1
	v_add_f32_dpp v230, v230, v230 row_half_mirror row_mask:0xf bank_mask:0xf
	v_div_scale_f32 v233, s[0:1], v227, v227, 1.0
	v_div_fmas_f32 v218, v226, v232, v229
	v_rcp_f32_e32 v234, v233
	v_div_fixup_f32 v218, v218, v228, 1.0
	s_waitcnt lgkmcnt(0)
	s_nop 1
	v_add_f32_dpp v228, v230, v230 row_mirror row_mask:0xf bank_mask:0xf
	v_fma_f32 v226, -v233, v234, 1.0
	v_fmac_f32_e32 v234, v226, v234
	v_div_scale_f32 v226, vcc, 1.0, v227, 1.0
	v_mul_f32_e32 v230, v226, v234
	s_waitcnt lgkmcnt(0)
	v_mov_b32_e32 v229, v228
	s_nop 1
	v_permlane16_swap_b32_e32 v228, v229
	v_add_f32_e32 v228, v228, v229
	v_fmamk_f32 v228, v228, 0x3c000000, v177
	v_fma_f32 v231, -v233, v230, v226
	v_mul_f32_e32 v229, 0x4f800000, v228
	v_cmp_gt_f32_e64 s[0:1], s49, v228
	v_fmac_f32_e32 v230, v231, v234
	v_fma_f32 v226, -v233, v230, v226
	v_cndmask_b32_e64 v228, v228, v229, s[0:1]
	v_sqrt_f32_e32 v229, v228
	v_fmac_f32_e32 v222, v140, v140
	v_fmac_f32_e32 v222, v184, v184
	v_fmac_f32_e32 v222, v196, v196
	v_add_u32_e32 v231, -1, v229
	s_waitcnt lgkmcnt(0)
	s_nop 1
	v_add_f32_dpp v219, v219, v219 quad_perm:[1,0,3,2] row_mask:0xf bank_mask:0xf
	v_fma_f32 v232, -v231, v229, v228
	v_cmp_ge_f32_e64 s[2:3], 0, v232
	v_add_u32_e32 v232, 1, v229
	v_mul_f32_e32 v223, v155, v155
	v_cndmask_b32_e64 v231, v229, v231, s[2:3]
	v_fma_f32 v229, -v232, v229, v228
	v_cmp_lt_f32_e64 s[2:3], 0, v229
	s_waitcnt lgkmcnt(0)
	s_nop 1
	v_add_f32_dpp v219, v219, v219 quad_perm:[2,3,0,1] row_mask:0xf bank_mask:0xf
	v_fmac_f32_e32 v223, v132, v132
	v_cndmask_b32_e64 v229, v231, v232, s[2:3]
	v_mul_f32_e32 v231, 0x37800000, v229
	v_cndmask_b32_e64 v229, v229, v231, s[0:1]
	v_cmp_class_f32_e64 s[0:1], v228, v176
	v_fmac_f32_e32 v223, v173, v173
	v_fmac_f32_e32 v223, v193, v193
	v_cndmask_b32_e64 v228, v229, v228, s[0:1]
	s_waitcnt lgkmcnt(0)
	s_nop 1
	v_add_f32_dpp v231, v219, v219 row_half_mirror row_mask:0xf bank_mask:0xf
	v_div_fmas_f32 v219, v226, v234, v230
	v_div_fixup_f32 v219, v219, v227, 1.0
	v_div_scale_f32 v229, s[0:1], v228, v228, 1.0
	s_waitcnt lgkmcnt(0)
	s_nop 1
	v_add_f32_dpp v227, v231, v231 row_mirror row_mask:0xf bank_mask:0xf
	v_rcp_f32_e32 v232, v229
	v_mul_f32_e32 v225, v145, v145
	v_fmac_f32_e32 v225, v125, v125
	s_waitcnt lgkmcnt(0)
	v_mov_b32_e32 v230, v227
	s_nop 1
	v_permlane16_swap_b32_e32 v227, v230
	v_add_f32_e32 v227, v227, v230
	v_fmamk_f32 v227, v227, 0x3c000000, v177
	v_mul_f32_e32 v230, 0x4f800000, v227
	v_cmp_gt_f32_e64 s[0:1], s49, v227
	v_fma_f32 v226, -v229, v232, 1.0
	v_fmac_f32_e32 v232, v226, v232
	v_cndmask_b32_e64 v227, v227, v230, s[0:1]
	v_div_scale_f32 v226, vcc, 1.0, v228, 1.0
	v_sqrt_f32_e32 v230, v227
	v_mul_f32_e32 v231, v226, v232
	v_fma_f32 v233, -v229, v231, v226
	v_fmac_f32_e32 v231, v233, v232
	v_fma_f32 v226, -v229, v231, v226
	v_add_u32_e32 v229, -1, v230
	s_waitcnt lgkmcnt(0)
	s_nop 1
	v_add_f32_dpp v221, v221, v221 quad_perm:[1,0,3,2] row_mask:0xf bank_mask:0xf
	v_fma_f32 v233, -v229, v230, v227
	v_cmp_ge_f32_e64 s[2:3], 0, v233
	v_add_u32_e32 v233, 1, v230
	v_fmac_f32_e32 v225, v164, v164
	v_cndmask_b32_e64 v229, v230, v229, s[2:3]
	v_fma_f32 v230, -v233, v230, v227
	v_cmp_lt_f32_e64 s[2:3], 0, v230
	s_waitcnt lgkmcnt(0)
	s_nop 1
	v_add_f32_dpp v221, v221, v221 quad_perm:[2,3,0,1] row_mask:0xf bank_mask:0xf
	v_fmac_f32_e32 v225, v189, v189
	v_cndmask_b32_e64 v229, v229, v233, s[2:3]
	v_mul_f32_e32 v230, 0x37800000, v229
	v_cndmask_b32_e64 v229, v229, v230, s[0:1]
	v_cmp_class_f32_e64 s[0:1], v227, v176
	v_mul_f32_e32 v224, v135, v135
	v_fmac_f32_e32 v224, v116, v116
	v_cndmask_b32_e64 v227, v229, v227, s[0:1]
	s_waitcnt lgkmcnt(0)
	s_nop 1
	v_add_f32_dpp v230, v221, v221 row_half_mirror row_mask:0xf bank_mask:0xf
	v_div_fmas_f32 v221, v226, v232, v231
	v_div_fixup_f32 v221, v221, v228, 1.0
	v_div_scale_f32 v229, s[0:1], v227, v227, 1.0
	s_waitcnt lgkmcnt(0)
	s_nop 1
	v_add_f32_dpp v228, v230, v230 row_mirror row_mask:0xf bank_mask:0xf
	v_rcp_f32_e32 v233, v229
	v_fmac_f32_e32 v224, v156, v156
	v_fmac_f32_e32 v224, v185, v185
	s_waitcnt lgkmcnt(0)
	v_mov_b32_e32 v230, v228
	s_nop 1
	v_permlane16_swap_b32_e32 v228, v230
	v_add_f32_e32 v228, v228, v230
	v_fmamk_f32 v228, v228, 0x3c000000, v177
	v_mul_f32_e32 v230, 0x4f800000, v228
	v_cmp_gt_f32_e64 s[0:1], s49, v228
	v_fma_f32 v226, -v229, v233, 1.0
	v_fmac_f32_e32 v233, v226, v233
	v_cndmask_b32_e64 v228, v228, v230, s[0:1]
	v_div_scale_f32 v226, vcc, 1.0, v227, 1.0
	v_sqrt_f32_e32 v230, v228
	v_mul_f32_e32 v231, v226, v233
	v_fma_f32 v232, -v229, v231, v226
	v_fmac_f32_e32 v231, v232, v233
	v_fma_f32 v226, -v229, v231, v226
	v_add_u32_e32 v229, -1, v230
	s_waitcnt lgkmcnt(0)
	s_nop 1
	v_add_f32_dpp v222, v222, v222 quad_perm:[1,0,3,2] row_mask:0xf bank_mask:0xf
	v_fma_f32 v232, -v229, v230, v228
	v_cmp_ge_f32_e64 s[2:3], 0, v232
	v_add_u32_e32 v232, 1, v230
	v_mul_f32_e32 v220, v127, v127
	v_cndmask_b32_e64 v229, v230, v229, s[2:3]
	v_fma_f32 v230, -v232, v230, v228
	v_cmp_lt_f32_e64 s[2:3], 0, v230
	s_waitcnt lgkmcnt(0)
	s_nop 1
	v_add_f32_dpp v222, v222, v222 quad_perm:[2,3,0,1] row_mask:0xf bank_mask:0xf
	v_fmac_f32_e32 v220, v107, v107
	v_cndmask_b32_e64 v229, v229, v232, s[2:3]
	v_mul_f32_e32 v230, 0x37800000, v229
	v_cndmask_b32_e64 v229, v229, v230, s[0:1]
	v_cmp_class_f32_e64 s[0:1], v228, v176
	v_fmac_f32_e32 v220, v146, v146
	v_fmac_f32_e32 v220, v170, v170
	v_cndmask_b32_e64 v228, v229, v228, s[0:1]
	s_waitcnt lgkmcnt(0)
; __device__ __forceinline__ void attn_unit_pp(int b, int h, int qb, int par, const bf16_t* __restrict__ QBp, const bf16_t* __restrict__ KBp, const bf16_t* __restrict__ VBp, ...
;     ...
;       for (int r = 0; r < 16; ++r) { const float v = o[d0][r] - lam * xs[(d0 * 16 + r) * 64]; o[d0][r] = v; ss[r] += v * v; }
; #pragma unroll
;     for (int r = 0; r < 16; ++r) { float s = ss[r];
; #pragma unroll
;       for (int x = 1; x < 32; x <<= 1) s += __builtin_bit_cast(float, __builtin_amdgcn_ds_bpermute((lane ^ x) << 2, __builtin_bit_cast(int, s)));
;       ss[r] = 1.0f / sqrtf(s * (1.0f / 128.0f) + 1e-5f); }
	s_nop 1
	v_add_f32_dpp v230, v222, v222 row_half_mirror row_mask:0xf bank_mask:0xf
	v_div_fmas_f32 v222, v226, v233, v231
	v_div_fixup_f32 v222, v222, v227, 1.0
	v_div_scale_f32 v229, s[0:1], v228, v228, 1.0
	s_waitcnt lgkmcnt(0)
	s_nop 1
	v_add_f32_dpp v227, v230, v230 row_mirror row_mask:0xf bank_mask:0xf
	v_rcp_f32_e32 v232, v229
	v_mul_f32_e32 v217, v118, v118
	v_fmac_f32_e32 v217, v101, v101
	s_waitcnt lgkmcnt(0)
	v_mov_b32_e32 v230, v227
	s_nop 1
	v_permlane16_swap_b32_e32 v227, v230
	v_add_f32_e32 v227, v227, v230
	v_fmamk_f32 v227, v227, 0x3c000000, v177
	v_mul_f32_e32 v230, 0x4f800000, v227
	v_cmp_gt_f32_e64 s[0:1], s49, v227
	v_fma_f32 v226, -v229, v232, 1.0
	v_fmac_f32_e32 v232, v226, v232
	v_cndmask_b32_e64 v227, v227, v230, s[0:1]
	v_div_scale_f32 v226, vcc, 1.0, v228, 1.0
	v_sqrt_f32_e32 v230, v227
	v_mul_f32_e32 v231, v226, v232
	v_fma_f32 v233, -v229, v231, v226
	v_fmac_f32_e32 v231, v233, v232
	v_fma_f32 v226, -v229, v231, v226
	v_add_u32_e32 v229, -1, v230
	s_waitcnt lgkmcnt(0)
	s_nop 1
	v_add_f32_dpp v223, v223, v223 quad_perm:[1,0,3,2] row_mask:0xf bank_mask:0xf
	v_fma_f32 v233, -v229, v230, v227
	v_cmp_ge_f32_e64 s[2:3], 0, v233
	v_add_u32_e32 v233, 1, v230
	v_fmac_f32_e32 v217, v136, v136
	v_cndmask_b32_e64 v229, v230, v229, s[2:3]
	v_fma_f32 v230, -v233, v230, v227
	v_cmp_lt_f32_e64 s[2:3], 0, v230
	s_waitcnt lgkmcnt(0)
	s_nop 1
	v_add_f32_dpp v223, v223, v223 quad_perm:[2,3,0,1] row_mask:0xf bank_mask:0xf
	v_fmac_f32_e32 v217, v160, v160
	v_cndmask_b32_e64 v229, v229, v233, s[2:3]
	v_mul_f32_e32 v230, 0x37800000, v229
	v_cndmask_b32_e64 v229, v229, v230, s[0:1]
	v_cmp_class_f32_e64 s[0:1], v227, v176
	v_mul_f32_e32 v214, v111, v111
	v_fmac_f32_e32 v214, v58, v58
	v_cndmask_b32_e64 v227, v229, v227, s[0:1]
	s_waitcnt lgkmcnt(0)
	s_nop 1
	v_add_f32_dpp v230, v223, v223 row_half_mirror row_mask:0xf bank_mask:0xf
	v_div_fmas_f32 v223, v226, v232, v231
	v_div_fixup_f32 v223, v223, v228, 1.0
	v_div_scale_f32 v229, s[0:1], v227, v227, 1.0
	s_waitcnt lgkmcnt(0)
	s_nop 1
	v_add_f32_dpp v228, v230, v230 row_mirror row_mask:0xf bank_mask:0xf
	v_rcp_f32_e32 v233, v229
	v_fmac_f32_e32 v214, v128, v128
	v_fmac_f32_e32 v214, v153, v153
	s_waitcnt lgkmcnt(0)
	v_mov_b32_e32 v230, v228
	s_nop 1
	v_permlane16_swap_b32_e32 v228, v230
	v_add_f32_e32 v228, v228, v230
	v_fmamk_f32 v228, v228, 0x3c000000, v177
	v_mul_f32_e32 v230, 0x4f800000, v228
	v_cmp_gt_f32_e64 s[0:1], s49, v228
	v_fma_f32 v226, -v229, v233, 1.0
	v_fmac_f32_e32 v233, v226, v233
	v_cndmask_b32_e64 v228, v228, v230, s[0:1]
	v_div_scale_f32 v226, vcc, 1.0, v227, 1.0
	v_sqrt_f32_e32 v230, v228
	v_mul_f32_e32 v231, v226, v233
	v_fma_f32 v232, -v229, v231, v226
	v_fmac_f32_e32 v231, v232, v233
	v_fma_f32 v226, -v229, v231, v226
	v_add_u32_e32 v229, -1, v230
	s_waitcnt lgkmcnt(0)
	s_nop 1
	v_add_f32_dpp v225, v225, v225 quad_perm:[1,0,3,2] row_mask:0xf bank_mask:0xf
	v_fma_f32 v232, -v229, v230, v228
	v_cmp_ge_f32_e64 s[2:3], 0, v232
	v_add_u32_e32 v232, 1, v230
	v_mul_f32_e32 v213, v103, v103
	v_cndmask_b32_e64 v229, v230, v229, s[2:3]
	v_fma_f32 v230, -v232, v230, v228
	v_cmp_lt_f32_e64 s[2:3], 0, v230
	s_waitcnt lgkmcnt(0)
	s_nop 1
	v_add_f32_dpp v225, v225, v225 quad_perm:[2,3,0,1] row_mask:0xf bank_mask:0xf
	v_fmac_f32_e32 v213, v51, v51
	v_cndmask_b32_e64 v229, v229, v232, s[2:3]
	v_mul_f32_e32 v230, 0x37800000, v229
	v_cndmask_b32_e64 v229, v229, v230, s[0:1]
	v_cmp_class_f32_e64 s[0:1], v228, v176
	v_fmac_f32_e32 v213, v119, v119
	v_fmac_f32_e32 v213, v142, v142
	v_cndmask_b32_e64 v228, v229, v228, s[0:1]
	s_waitcnt lgkmcnt(0)
	s_nop 1
	v_add_f32_dpp v230, v225, v225 row_half_mirror row_mask:0xf bank_mask:0xf
	v_div_fmas_f32 v225, v226, v233, v231
	v_div_fixup_f32 v225, v225, v227, 1.0
	v_div_scale_f32 v229, s[0:1], v228, v228, 1.0
	s_waitcnt lgkmcnt(0)
	s_nop 1
	v_add_f32_dpp v227, v230, v230 row_mirror row_mask:0xf bank_mask:0xf
	v_rcp_f32_e32 v232, v229
	v_mul_f32_e32 v211, v61, v61
	v_fmac_f32_e32 v211, v46, v46
	s_waitcnt lgkmcnt(0)
	v_mov_b32_e32 v230, v227
	s_nop 1
	v_permlane16_swap_b32_e32 v227, v230
	v_add_f32_e32 v227, v227, v230
	v_fmamk_f32 v227, v227, 0x3c000000, v177
	v_mul_f32_e32 v230, 0x4f800000, v227
	v_cmp_gt_f32_e64 s[0:1], s49, v227
	v_fma_f32 v226, -v229, v232, 1.0
	v_fmac_f32_e32 v232, v226, v232
	v_cndmask_b32_e64 v227, v227, v230, s[0:1]
	v_div_scale_f32 v226, vcc, 1.0, v228, 1.0
	v_sqrt_f32_e32 v230, v227
	v_mul_f32_e32 v231, v226, v232
	v_fma_f32 v233, -v229, v231, v226
	v_fmac_f32_e32 v231, v233, v232
	v_fma_f32 v226, -v229, v231, v226
	v_add_u32_e32 v229, -1, v230
	s_waitcnt lgkmcnt(0)
	s_nop 1
	v_add_f32_dpp v224, v224, v224 quad_perm:[1,0,3,2] row_mask:0xf bank_mask:0xf
	v_fma_f32 v233, -v229, v230, v227
	v_cmp_ge_f32_e64 s[2:3], 0, v233
	v_add_u32_e32 v233, 1, v230
	v_fmac_f32_e32 v211, v112, v112
	v_cndmask_b32_e64 v229, v230, v229, s[2:3]
	v_fma_f32 v230, -v233, v230, v227
	v_cmp_lt_f32_e64 s[2:3], 0, v230
	s_waitcnt lgkmcnt(0)
	s_nop 1
	v_add_f32_dpp v224, v224, v224 quad_perm:[2,3,0,1] row_mask:0xf bank_mask:0xf
	v_fmac_f32_e32 v211, v144, v144
	v_cndmask_b32_e64 v229, v229, v233, s[2:3]
	v_mul_f32_e32 v230, 0x37800000, v229
	v_cndmask_b32_e64 v229, v229, v230, s[0:1]
	v_cmp_class_f32_e64 s[0:1], v227, v176
	s_waitcnt vmcnt(61)
	v_lshlrev_b32_e32 v162, 16, v162
	v_exp_f32_e32 v163, v163
	v_cndmask_b32_e64 v227, v229, v227, s[0:1]
	s_waitcnt lgkmcnt(0)
	s_nop 1
	v_add_f32_dpp v230, v224, v224 row_half_mirror row_mask:0xf bank_mask:0xf
	v_div_fmas_f32 v224, v226, v232, v231
	v_div_fixup_f32 v224, v224, v228, 1.0
	v_div_scale_f32 v229, s[0:1], v227, v227, 1.0
	s_waitcnt lgkmcnt(0)
; __device__ __forceinline__ float sigm_(float x) { return __builtin_amdgcn_rcpf(1.0f + __builtin_amdgcn_exp2f(-1.4426950408889634f * x)); }
; __device__ __forceinline__ void attn_unit_pp(int b, int h, int qb, int par, const bf16_t* __restrict__ QBp, const bf16_t* __restrict__ KBp, const bf16_t* __restrict__ VBp, ...
;     ...
;       for (int r = 0; r < 16; ++r) { const float v = o[d0][r] - lam * xs[(d0 * 16 + r) * 64]; o[d0][r] = v; ss[r] += v * v; }
; #pragma unroll
;     for (int r = 0; r < 16; ++r) { float s = ss[r];
; #pragma unroll
;       for (int x = 1; x < 32; x <<= 1) s += __builtin_bit_cast(float, __builtin_amdgcn_ds_bpermute((lane ^ x) << 2, __builtin_bit_cast(int, s)));
;       ss[r] = 1.0f / sqrtf(s * (1.0f / 128.0f) + 1e-5f); }
;     ...
;       for (int d0 = 0; d0 < 4; ++d0) { const float ga = __uint_as_float(gate16[r * 4 + d0] << 16); o[d0][r] = o[d0][r] * ss[r] * sg[d0] * sigm_(ga); }
	s_nop 1
	v_add_f32_dpp v228, v230, v230 row_mirror row_mask:0xf bank_mask:0xf
	v_rcp_f32_e32 v233, v229
	v_mul_f32_e32 v162, 0xbfb8aa3b, v162
	s_waitcnt vmcnt(60)
	v_lshlrev_b32_e32 v159, 16, v159
	s_waitcnt lgkmcnt(0)
	v_mov_b32_e32 v230, v228
	s_nop 1
	v_permlane16_swap_b32_e32 v228, v230
	v_add_f32_e32 v228, v228, v230
	v_fmamk_f32 v228, v228, 0x3c000000, v177
	v_mul_f32_e32 v230, 0x4f800000, v228
	v_cmp_gt_f32_e64 s[0:1], s49, v228
	v_fma_f32 v226, -v229, v233, 1.0
	v_fmac_f32_e32 v233, v226, v233
	v_cndmask_b32_e64 v228, v228, v230, s[0:1]
	v_div_scale_f32 v226, vcc, 1.0, v227, 1.0
	v_sqrt_f32_e32 v230, v228
	v_mul_f32_e32 v231, v226, v233
	v_fma_f32 v232, -v229, v231, v226
	v_fmac_f32_e32 v231, v232, v233
	v_fma_f32 v226, -v229, v231, v226
	v_add_u32_e32 v229, -1, v230
	s_waitcnt lgkmcnt(0)
	s_nop 1
	v_add_f32_dpp v220, v220, v220 quad_perm:[1,0,3,2] row_mask:0xf bank_mask:0xf
	v_fma_f32 v232, -v229, v230, v228
	v_cmp_ge_f32_e64 s[2:3], 0, v232
	v_add_u32_e32 v232, 1, v230
	v_add_f32_e32 v163, 1.0, v163
	v_cndmask_b32_e64 v229, v230, v229, s[2:3]
	v_fma_f32 v230, -v232, v230, v228
	v_cmp_lt_f32_e64 s[2:3], 0, v230
	s_waitcnt lgkmcnt(0)
	s_nop 1
	v_add_f32_dpp v220, v220, v220 quad_perm:[2,3,0,1] row_mask:0xf bank_mask:0xf
	v_mul_f32_e32 v159, 0xbfb8aa3b, v159
	v_cndmask_b32_e64 v229, v229, v232, s[2:3]
	v_mul_f32_e32 v230, 0x37800000, v229
	v_cndmask_b32_e64 v229, v229, v230, s[0:1]
	v_cmp_class_f32_e64 s[0:1], v228, v176
	s_waitcnt vmcnt(58)
	v_lshlrev_b32_e32 v154, 16, v154
	v_lshlrev_b32_e32 v157, 16, v157
	v_cndmask_b32_e64 v228, v229, v228, s[0:1]
	s_waitcnt lgkmcnt(0)
	s_nop 1
	v_add_f32_dpp v230, v220, v220 row_half_mirror row_mask:0xf bank_mask:0xf
	v_div_fmas_f32 v220, v226, v233, v231
	v_div_fixup_f32 v220, v220, v227, 1.0
	v_div_scale_f32 v229, s[0:1], v228, v228, 1.0
	s_waitcnt lgkmcnt(0)
	s_nop 1
	v_add_f32_dpp v227, v230, v230 row_mirror row_mask:0xf bank_mask:0xf
	v_rcp_f32_e32 v232, v229
	v_mul_f32_e32 v154, 0xbfb8aa3b, v154
	s_waitcnt vmcnt(57)
	v_lshlrev_b32_e32 v152, 16, v152
	s_waitcnt lgkmcnt(0)
	v_mov_b32_e32 v230, v227
	s_nop 1
	v_permlane16_swap_b32_e32 v227, v230
	v_add_f32_e32 v227, v227, v230
	v_fmamk_f32 v227, v227, 0x3c000000, v177
	v_mul_f32_e32 v230, 0x4f800000, v227
	v_cmp_gt_f32_e64 s[0:1], s49, v227
	v_fma_f32 v226, -v229, v232, 1.0
	v_fmac_f32_e32 v232, v226, v232
	v_cndmask_b32_e64 v227, v227, v230, s[0:1]
	v_div_scale_f32 v226, vcc, 1.0, v228, 1.0
	v_sqrt_f32_e32 v230, v227
	v_mul_f32_e32 v231, v226, v232
	v_fma_f32 v233, -v229, v231, v226
	v_fmac_f32_e32 v231, v233, v232
	v_fma_f32 v226, -v229, v231, v226
	v_add_u32_e32 v229, -1, v230
	s_waitcnt lgkmcnt(0)
	s_nop 1
	v_add_f32_dpp v217, v217, v217 quad_perm:[1,0,3,2] row_mask:0xf bank_mask:0xf
	v_fma_f32 v233, -v229, v230, v227
	v_cmp_ge_f32_e64 s[2:3], 0, v233
	v_add_u32_e32 v233, 1, v230
	v_mul_f32_e32 v157, 0xbfb8aa3b, v157
	v_cndmask_b32_e64 v229, v230, v229, s[2:3]
	v_fma_f32 v230, -v233, v230, v227
	v_cmp_lt_f32_e64 s[2:3], 0, v230
	s_waitcnt lgkmcnt(0)
	s_nop 1
	v_add_f32_dpp v217, v217, v217 quad_perm:[2,3,0,1] row_mask:0xf bank_mask:0xf
	v_exp_f32_e32 v154, v154
	v_cndmask_b32_e64 v229, v229, v233, s[2:3]
	v_mul_f32_e32 v230, 0x37800000, v229
	v_cndmask_b32_e64 v229, v229, v230, s[0:1]
	v_cmp_class_f32_e64 s[0:1], v227, v176
	v_mul_f32_e32 v152, 0xbfb8aa3b, v152
	s_waitcnt vmcnt(56)
	v_lshlrev_b32_e32 v149, 16, v149
	v_cndmask_b32_e64 v227, v229, v227, s[0:1]
	s_waitcnt lgkmcnt(0)
	s_nop 1
	v_add_f32_dpp v230, v217, v217 row_half_mirror row_mask:0xf bank_mask:0xf
	v_div_fmas_f32 v217, v226, v232, v231
	v_div_fixup_f32 v217, v217, v228, 1.0
	v_div_scale_f32 v229, s[0:1], v227, v227, 1.0
	s_waitcnt lgkmcnt(0)
	s_nop 1
	v_add_f32_dpp v228, v230, v230 row_mirror row_mask:0xf bank_mask:0xf
	v_rcp_f32_e32 v233, v229
	v_add_f32_e32 v154, 1.0, v154
	v_mul_f32_e32 v149, 0xbfb8aa3b, v149
	s_waitcnt lgkmcnt(0)
	v_mov_b32_e32 v230, v228
	s_nop 1
	v_permlane16_swap_b32_e32 v228, v230
	v_add_f32_e32 v228, v228, v230
	v_fmamk_f32 v228, v228, 0x3c000000, v177
	v_mul_f32_e32 v230, 0x4f800000, v228
	v_cmp_gt_f32_e64 s[0:1], s49, v228
	v_fma_f32 v226, -v229, v233, 1.0
	v_fmac_f32_e32 v233, v226, v233
	v_cndmask_b32_e64 v228, v228, v230, s[0:1]
	v_div_scale_f32 v226, vcc, 1.0, v227, 1.0
	v_sqrt_f32_e32 v230, v228
	v_mul_f32_e32 v231, v226, v233
	v_fma_f32 v232, -v229, v231, v226
	v_fmac_f32_e32 v231, v232, v233
	v_fma_f32 v226, -v229, v231, v226
	v_add_u32_e32 v229, -1, v230
	s_waitcnt lgkmcnt(0)
	s_nop 1
	v_add_f32_dpp v214, v214, v214 quad_perm:[1,0,3,2] row_mask:0xf bank_mask:0xf
	v_fma_f32 v232, -v229, v230, v228
	v_cmp_ge_f32_e64 s[2:3], 0, v232
	v_add_u32_e32 v232, 1, v230
	v_lshlrev_b32_e32 v165, 16, v165
	v_cndmask_b32_e64 v229, v230, v229, s[2:3]
	v_fma_f32 v230, -v232, v230, v228
	v_cmp_lt_f32_e64 s[2:3], 0, v230
	s_waitcnt lgkmcnt(0)
	s_nop 1
	v_add_f32_dpp v214, v214, v214 quad_perm:[2,3,0,1] row_mask:0xf bank_mask:0xf
	v_mul_f32_e32 v165, 0xbfb8aa3b, v165
	v_cndmask_b32_e64 v229, v229, v232, s[2:3]
	v_mul_f32_e32 v230, 0x37800000, v229
	v_cndmask_b32_e64 v229, v229, v230, s[0:1]
	v_cmp_class_f32_e64 s[0:1], v228, v176
	s_waitcnt vmcnt(55)
	v_lshlrev_b32_e32 v151, 16, v151
	s_waitcnt vmcnt(54)
	v_lshlrev_b32_e32 v148, 16, v148
	v_cndmask_b32_e64 v228, v229, v228, s[0:1]
	s_waitcnt lgkmcnt(0)
	s_nop 1
	v_add_f32_dpp v230, v214, v214 row_half_mirror row_mask:0xf bank_mask:0xf
	v_div_fmas_f32 v214, v226, v233, v231
	v_div_fixup_f32 v214, v214, v227, 1.0
	v_div_scale_f32 v229, s[0:1], v228, v228, 1.0
	s_waitcnt lgkmcnt(0)
	s_nop 1
	v_add_f32_dpp v227, v230, v230 row_mirror row_mask:0xf bank_mask:0xf
	v_rcp_f32_e32 v232, v229
	v_exp_f32_e32 v165, v165
	s_waitcnt lgkmcnt(0)
; __device__ __forceinline__ void attn_unit_pp(int b, int h, int qb, int par, const bf16_t* __restrict__ QBp, const bf16_t* __restrict__ KBp, const bf16_t* __restrict__ VBp, ...
;     ...
;     for (int r = 0; r < 16; ++r) { float s = ss[r];
; #pragma unroll
;       for (int x = 1; x < 32; x <<= 1) s += __builtin_bit_cast(float, __builtin_amdgcn_ds_bpermute((lane ^ x) << 2, __builtin_bit_cast(int, s)));
;       ss[r] = 1.0f / sqrtf(s * (1.0f / 128.0f) + 1e-5f); }
;     float sg[4];
; #pragma unroll
;     for (int d0 = 0; d0 < 4; ++d0) sg[d0] = sub_g[d0 * 32 + r32] * 0.8f;
	v_mov_b32_e32 v230, v227
	s_nop 1
	v_permlane16_swap_b32_e32 v227, v230
	v_add_f32_e32 v227, v227, v230
	v_fmamk_f32 v227, v227, 0x3c000000, v177
	v_mul_f32_e32 v230, 0x4f800000, v227
	v_cmp_gt_f32_e64 s[0:1], s49, v227
	v_fma_f32 v226, -v229, v232, 1.0
	v_fmac_f32_e32 v232, v226, v232
	v_cndmask_b32_e64 v227, v227, v230, s[0:1]
	v_div_scale_f32 v226, vcc, 1.0, v228, 1.0
	v_sqrt_f32_e32 v230, v227
	v_mul_f32_e32 v231, v226, v232
	v_fma_f32 v233, -v229, v231, v226
	v_fmac_f32_e32 v231, v233, v232
	v_fma_f32 v226, -v229, v231, v226
	v_add_u32_e32 v229, -1, v230
	s_waitcnt lgkmcnt(0)
	s_nop 1
	v_add_f32_dpp v213, v213, v213 quad_perm:[1,0,3,2] row_mask:0xf bank_mask:0xf
	v_fma_f32 v233, -v229, v230, v227
	v_cmp_ge_f32_e64 s[2:3], 0, v233
	v_add_u32_e32 v233, 1, v230
	s_waitcnt lgkmcnt(0)
	s_nop 1
	v_add_f32_dpp v183, v211, v211 quad_perm:[1,0,3,2] row_mask:0xf bank_mask:0xf
	v_cndmask_b32_e64 v229, v230, v229, s[2:3]
	v_fma_f32 v230, -v233, v230, v227
	v_cmp_lt_f32_e64 s[2:3], 0, v230
	s_waitcnt lgkmcnt(0)
	s_nop 1
	v_add_f32_dpp v213, v213, v213 quad_perm:[2,3,0,1] row_mask:0xf bank_mask:0xf
	v_cndmask_b32_e64 v229, v229, v233, s[2:3]
	v_mul_f32_e32 v230, 0x37800000, v229
	v_cndmask_b32_e64 v229, v229, v230, s[0:1]
	v_cmp_class_f32_e64 s[0:1], v227, v176
	s_waitcnt lgkmcnt(0)
	s_nop 1
	v_add_f32_dpp v182, v183, v183 quad_perm:[2,3,0,1] row_mask:0xf bank_mask:0xf
	v_cndmask_b32_e64 v227, v229, v227, s[0:1]
	s_waitcnt lgkmcnt(0)
	s_nop 1
	v_add_f32_dpp v230, v213, v213 row_half_mirror row_mask:0xf bank_mask:0xf
	v_div_fmas_f32 v213, v226, v232, v231
	v_lshlrev_b32_e32 v232, 2, v179
	v_div_fixup_f32 v213, v213, v228, 1.0
	v_div_scale_f32 v229, s[0:1], v227, v227, 1.0
	s_waitcnt lgkmcnt(0)
	s_nop 1
	v_add_f32_dpp v228, v230, v230 row_mirror row_mask:0xf bank_mask:0xf
	global_load_dword v234, v232, s[54:55]
	global_load_dword v235, v232, s[54:55] offset:128
	global_load_dword v236, v232, s[54:55] offset:256
	v_rcp_f32_e32 v233, v229
	global_load_dword v237, v232, s[54:55] offset:384
	s_nop 1
	v_add_f32_dpp v181, v182, v182 row_half_mirror row_mask:0xf bank_mask:0xf
	s_waitcnt lgkmcnt(0)
	v_mov_b32_e32 v230, v228
	s_nop 1
	v_permlane16_swap_b32_e32 v228, v230
	v_add_f32_e32 v228, v228, v230
	v_fmamk_f32 v228, v228, 0x3c000000, v177
	v_mul_f32_e32 v230, 0x4f800000, v228
	v_cmp_gt_f32_e64 s[0:1], s49, v228
	v_fma_f32 v226, -v229, v233, 1.0
	v_fmac_f32_e32 v233, v226, v233
	v_cndmask_b32_e64 v228, v228, v230, s[0:1]
	v_div_scale_f32 v226, vcc, 1.0, v227, 1.0
	v_sqrt_f32_e32 v230, v228
	v_mul_f32_e32 v231, v226, v233
	v_fma_f32 v232, -v229, v231, v226
	v_fmac_f32_e32 v231, v232, v233
	v_fma_f32 v226, -v229, v231, v226
	v_add_u32_e32 v229, -1, v230
	v_fma_f32 v232, -v229, v230, v228
	v_cmp_ge_f32_e64 s[2:3], 0, v232
	v_add_u32_e32 v232, 1, v230
	s_waitcnt lgkmcnt(0)
	s_nop 1
	v_add_f32_dpp v180, v181, v181 row_mirror row_mask:0xf bank_mask:0xf
	v_cndmask_b32_e64 v229, v230, v229, s[2:3]
	v_fma_f32 v230, -v232, v230, v228
	v_cmp_lt_f32_e64 s[2:3], 0, v230
	v_div_fmas_f32 v182, v226, v233, v231
	v_cndmask_b32_e64 v211, v229, v232, s[2:3]
	v_mul_f32_e32 v229, 0x37800000, v211
	v_cndmask_b32_e64 v211, v211, v229, s[0:1]
	v_cmp_class_f32_e64 s[0:1], v228, v176
	s_waitcnt lgkmcnt(0)
	v_mov_b32_e32 v169, v180
	s_nop 1
	v_permlane16_swap_b32_e32 v180, v169
	v_add_f32_e32 v169, v180, v169
	v_fmamk_f32 v169, v169, 0x3c000000, v177
	v_cndmask_b32_e64 v183, v211, v228, s[0:1]
	v_div_scale_f32 v211, s[0:1], v183, v183, 1.0
	v_rcp_f32_e32 v228, v211
	v_mul_f32_e32 v180, 0x4f800000, v169
	v_cmp_gt_f32_e64 s[0:1], s49, v169
	v_div_fixup_f32 v232, v182, v227, 1.0
	v_fma_f32 v182, -v211, v228, 1.0
	v_cndmask_b32_e64 v169, v169, v180, s[0:1]
	v_fmac_f32_e32 v228, v182, v228
	v_div_scale_f32 v181, vcc, 1.0, v183, 1.0
	v_sqrt_f32_e32 v180, v169
	v_mul_f32_e32 v182, v181, v228
	v_fma_f32 v226, -v211, v182, v181
	v_fmac_f32_e32 v182, v226, v228
	v_fma_f32 v181, -v211, v182, v181
	v_add_u32_e32 v211, -1, v180
	v_fma_f32 v226, -v211, v180, v169
	v_cmp_ge_f32_e64 s[2:3], 0, v226
	v_add_u32_e32 v226, 1, v180
	v_div_fmas_f32 v181, v181, v228, v182
	v_cndmask_b32_e64 v211, v180, v211, s[2:3]
	v_fma_f32 v180, -v226, v180, v169
	v_cmp_lt_f32_e64 s[2:3], 0, v180
	v_div_fixup_f32 v230, v181, v183, 1.0
	v_mul_f32_e32 v151, 0xbfb8aa3b, v151
	v_cndmask_b32_e64 v180, v211, v226, s[2:3]
	v_mul_f32_e32 v211, 0x37800000, v180
	v_cndmask_b32_e64 v180, v180, v211, s[0:1]
	v_cmp_class_f32_e64 s[0:1], v169, v176
	v_mul_f32_e32 v148, 0xbfb8aa3b, v148
	s_waitcnt vmcnt(57)
	v_lshlrev_b32_e32 v147, 16, v147
	v_cndmask_b32_e64 v169, v180, v169, s[0:1]
	v_div_scale_f32 v180, s[0:1], v169, v169, 1.0
	v_rcp_f32_e32 v211, v180
	s_waitcnt vmcnt(55)
	v_lshlrev_b32_e32 v141, 16, v141
	v_exp_f32_e32 v148, v148
	v_mul_f32_e32 v147, 0xbfb8aa3b, v147
	v_fma_f32 v181, -v180, v211, 1.0
	v_fmac_f32_e32 v211, v181, v211
	v_div_scale_f32 v181, vcc, 1.0, v169, 1.0
	v_mul_f32_e32 v182, v181, v211
	v_fma_f32 v183, -v180, v182, v181
	v_fmac_f32_e32 v182, v183, v211
	v_fma_f32 v180, -v180, v182, v181
	v_div_fmas_f32 v180, v180, v211, v182
	v_div_fixup_f32 v226, v180, v169, 1.0
	v_exp_f32_e32 v180, v162
	s_waitcnt vmcnt(3)
; __device__ __forceinline__ float sigm_(float x) { return __builtin_amdgcn_rcpf(1.0f + __builtin_amdgcn_exp2f(-1.4426950408889634f * x)); }
; __device__ __forceinline__ void attn_unit_pp(int b, int h, int qb, int par, const bf16_t* __restrict__ QBp, const bf16_t* __restrict__ KBp, const bf16_t* __restrict__ VBp, ...
;     ...
;       ss[r] = 1.0f / sqrtf(s * (1.0f / 128.0f) + 1e-5f); }
;     float sg[4];
; #pragma unroll
;     for (int d0 = 0; d0 < 4; ++d0) sg[d0] = sub_g[d0 * 32 + r32] * 0.8f;
; #pragma unroll
;     for (int r = 0; r < 16; ++r)
; #pragma unroll
;       for (int d0 = 0; d0 < 4; ++d0) { const float ga = __uint_as_float(gate16[r * 4 + d0] << 16); o[d0][r] = o[d0][r] * ss[r] * sg[d0] * sigm_(ga); }
	v_mul_f32_e32 v231, 0x3f4ccccd, v234
	v_mul_f32_e32 v169, v198, v215
	v_mul_f32_e32 v198, v169, v231
	v_rcp_f32_e32 v169, v163
	v_add_f32_e32 v163, 1.0, v180
	v_exp_f32_e32 v180, v159
	v_exp_f32_e32 v181, v157
	v_exp_f32_e32 v182, v152
	v_exp_f32_e32 v183, v151
	v_add_f32_e32 v180, 1.0, v180
	v_rcp_f32_e32 v157, v180
	v_mul_f32_e32 v180, v194, v216
	v_mul_f32_e32 v194, v180, v231
	v_add_f32_e32 v180, 1.0, v181
	v_rcp_f32_e32 v181, v154
	v_add_f32_e32 v154, 1.0, v182
	v_exp_f32_e32 v182, v149
	v_mul_f32_e32 v141, 0xbfb8aa3b, v141
	v_add_f32_e32 v165, 1.0, v165
	v_lshlrev_b32_e32 v143, 16, v143
	v_add_f32_e32 v182, 1.0, v182
	v_rcp_f32_e32 v151, v182
	v_mul_f32_e32 v182, v190, v218
	v_exp_f32_e32 v190, v147
	v_mul_f32_e32 v147, v205, v218
	v_exp_f32_e32 v205, v141
	v_lshlrev_b32_e32 v139, 16, v139
	v_rcp_f32_e32 v211, v165
	v_mul_f32_e32 v165, v202, v215
	v_rcp_f32_e32 v202, v180
	v_mul_f32_e32 v180, v199, v216
	v_mul_f32_e32 v199, v182, v231
	v_add_f32_e32 v182, 1.0, v183
	v_add_f32_e32 v148, 1.0, v148
	v_mul_f32_e32 v143, 0xbfb8aa3b, v143
	v_mul_f32_e32 v186, v186, v219
	v_mul_f32_e32 v139, 0xbfb8aa3b, v139
	v_lshlrev_b32_e32 v138, 16, v138
	v_mul_f32_e32 v152, v207, v216
	v_rcp_f32_e32 v207, v182
	v_mul_f32_e32 v182, v195, v218
	v_rcp_f32_e32 v183, v148
	v_add_f32_e32 v148, 1.0, v190
	v_exp_f32_e32 v190, v143
	v_mul_f32_e32 v195, v186, v231
	v_add_f32_e32 v186, 1.0, v205
	v_exp_f32_e32 v139, v139
	v_mul_f32_e32 v138, 0xbfb8aa3b, v138
	v_rcp_f32_e32 v205, v186
	v_mul_f32_e32 v186, v191, v219
	v_exp_f32_e32 v191, v138
	v_lshlrev_b32_e32 v134, 16, v134
	v_add_f32_e32 v190, 1.0, v190
	v_add_f32_e32 v139, 1.0, v139
	v_mul_f32_e32 v134, 0xbfb8aa3b, v134
	v_lshlrev_b32_e32 v137, 16, v137
	v_lshlrev_b32_e32 v133, 16, v133
	v_rcp_f32_e32 v141, v190
	v_rcp_f32_e32 v190, v139
	v_add_f32_e32 v139, 1.0, v191
	v_exp_f32_e32 v191, v134
	v_mul_f32_e32 v137, 0xbfb8aa3b, v137
	v_mul_f32_e32 v133, 0xbfb8aa3b, v133
	v_lshlrev_b32_e32 v131, 16, v131
	v_mul_f32_e32 v138, v201, v219
	v_exp_f32_e32 v201, v137
	v_exp_f32_e32 v133, v133
	v_mul_f32_e32 v131, 0xbfb8aa3b, v131
	v_mul_f32_e32 v134, v206, v219
	v_exp_f32_e32 v206, v131
	v_add_f32_e32 v191, 1.0, v191
	v_mul_f32_e32 v171, v171, v221
	v_lshlrev_b32_e32 v124, 16, v124
	v_lshlrev_b32_e32 v122, 16, v122
	v_rcp_f32_e32 v137, v191
	v_mul_f32_e32 v191, v171, v231
	v_add_f32_e32 v171, 1.0, v201
	v_add_f32_e32 v133, 1.0, v133
	v_mul_f32_e32 v124, 0xbfb8aa3b, v124
	v_mul_f32_e32 v122, 0xbfb8aa3b, v122
	v_rcp_f32_e32 v201, v171
	v_mul_f32_e32 v171, v187, v221
	v_rcp_f32_e32 v187, v133
	v_add_f32_e32 v133, 1.0, v206
	v_lshlrev_b32_e32 v130, 16, v130
	v_exp_f32_e32 v206, v124
	v_mul_f32_e32 v124, v192, v222
	v_exp_f32_e32 v192, v122
	v_mul_f32_e32 v130, 0xbfb8aa3b, v130
	v_lshlrev_b32_e32 v129, 16, v129
	v_lshlrev_b32_e32 v126, 16, v126
	v_mul_f32_e32 v131, v197, v221
	v_exp_f32_e32 v197, v130
	v_mul_f32_e32 v129, 0xbfb8aa3b, v129
	v_mul_f32_e32 v126, 0xbfb8aa3b, v126
	v_lshlrev_b32_e32 v123, 16, v123
	v_lshlrev_b32_e32 v121, 16, v121
	v_mul_f32_e32 v130, v204, v221
	v_exp_f32_e32 v204, v129
	v_exp_f32_e32 v126, v126
	v_mul_f32_e32 v123, 0xbfb8aa3b, v123
	v_mul_f32_e32 v121, 0xbfb8aa3b, v121
	v_lshlrev_b32_e32 v120, 16, v120
	v_lshlrev_b32_e32 v117, 16, v117
	v_mul_f32_e32 v122, v203, v222
	v_add_f32_e32 v192, 1.0, v192
	v_exp_f32_e32 v203, v123
	v_exp_f32_e32 v121, v121
	v_mul_f32_e32 v120, 0xbfb8aa3b, v120
	v_mul_f32_e32 v117, 0xbfb8aa3b, v117
	v_rcp_f32_e32 v123, v192
	v_exp_f32_e32 v192, v120
	v_mul_f32_e32 v120, v188, v223
	v_exp_f32_e32 v188, v117
	v_add_f32_e32 v197, 1.0, v197
	v_mul_f32_e32 v161, v161, v222
	v_rcp_f32_e32 v129, v197
	v_mul_f32_e32 v197, v161, v231
	v_add_f32_e32 v161, 1.0, v204
	v_add_f32_e32 v126, 1.0, v126
	v_mul_f32_e32 v150, v150, v223
	v_lshlrev_b32_e32 v115, 16, v115
	v_lshlrev_b32_e32 v114, 16, v114
	v_rcp_f32_e32 v204, v161
	v_mul_f32_e32 v161, v172, v222
	v_rcp_f32_e32 v172, v126
	v_add_f32_e32 v126, 1.0, v206
	v_mul_f32_e32 v206, v150, v231
	v_add_f32_e32 v150, 1.0, v203
	v_add_f32_e32 v121, 1.0, v121
	v_mul_f32_e32 v115, 0xbfb8aa3b, v115
	v_mul_f32_e32 v114, 0xbfb8aa3b, v114
	v_lshlrev_b32_e32 v113, 16, v113
	v_lshlrev_b32_e32 v109, 16, v109
	v_rcp_f32_e32 v203, v150
	v_mul_f32_e32 v150, v167, v223
	v_rcp_f32_e32 v167, v121
	v_add_f32_e32 v121, 1.0, v192
	v_add_f32_e32 v188, 1.0, v188
	v_exp_f32_e32 v192, v115
	v_exp_f32_e32 v114, v114
	v_mul_f32_e32 v113, 0xbfb8aa3b, v113
	v_mul_f32_e32 v109, 0xbfb8aa3b, v109
	v_rcp_f32_e32 v115, v188
	v_exp_f32_e32 v188, v113
	v_mul_f32_e32 v113, v184, v225
	v_exp_f32_e32 v184, v109
	v_mul_f32_e32 v140, v140, v225
	v_lshlrev_b32_e32 v110, 16, v110
	v_lshlrev_b32_e32 v108, 16, v108
	v_mul_f32_e32 v117, v200, v223
	v_mul_f32_e32 v200, v140, v231
	v_add_f32_e32 v140, 1.0, v192
	v_add_f32_e32 v114, 1.0, v114
	v_mul_f32_e32 v110, 0xbfb8aa3b, v110
	v_mul_f32_e32 v108, 0xbfb8aa3b, v108
	v_lshlrev_b32_e32 v106, 16, v106
	v_mul_f32_e32 v143, v208, v218
	v_rcp_f32_e32 v208, v140
	v_mul_f32_e32 v140, v158, v225
	v_rcp_f32_e32 v158, v114
	v_add_f32_e32 v114, 1.0, v188
	v_add_f32_e32 v184, 1.0, v184
	v_exp_f32_e32 v188, v110
	v_exp_f32_e32 v108, v108
	v_mul_f32_e32 v106, 0xbfb8aa3b, v106
	v_rcp_f32_e32 v110, v184
	v_exp_f32_e32 v184, v106
	v_lshlrev_b32_e32 v105, 16, v105
	v_mul_f32_e32 v132, v132, v224
	v_mul_f32_e32 v105, 0xbfb8aa3b, v105
	v_lshlrev_b32_e32 v104, 16, v104
	v_mul_f32_e32 v109, v196, v225
	v_mul_f32_e32 v196, v132, v231
	v_add_f32_e32 v132, 1.0, v188
	v_add_f32_e32 v108, 1.0, v108
	v_mul_f32_e32 v106, v173, v224
	v_exp_f32_e32 v173, v105
	v_mul_f32_e32 v104, 0xbfb8aa3b, v104
	v_mul_f32_e32 v162, v209, v215
	v_rcp_f32_e32 v209, v132
; __device__ __forceinline__ float sigm_(float x) { return __builtin_amdgcn_rcpf(1.0f + __builtin_amdgcn_exp2f(-1.4426950408889634f * x)); }
; __device__ __forceinline__ void attn_unit_pp(int b, int h, int qb, int par, const bf16_t* __restrict__ QBp, const bf16_t* __restrict__ KBp, const bf16_t* __restrict__ VBp, ...
;     ...
;     for (int r = 0; r < 16; ++r)
; #pragma unroll
;       for (int d0 = 0; d0 < 4; ++d0) { const float ga = __uint_as_float(gate16[r * 4 + d0] << 16); o[d0][r] = o[d0][r] * ss[r] * sg[d0] * sigm_(ga); }
;     __syncthreads();
; #pragma unroll
;     for (int d0 = 0; d0 < 4; ++d0)
; #pragma unroll
;       for (int r = 0; r < 16; ++r) { const int ro = (r & 3) + 8 * (r >> 2);
;         const float val = o[d0][r] + pgs[(d0 * 16 + r) * 64];
;         unsigned u = __float_as_uint(val); u = (u + 0x7fffu + ((u >> 16) & 1u)) >> 16;
;         MIX_ST(ro, d0 * 32, (unsigned short)u); }
	v_mul_f32_e32 v132, v155, v224
	v_rcp_f32_e32 v155, v108
	v_add_f32_e32 v108, 1.0, v184
	v_exp_f32_e32 v184, v104
	v_lshlrev_b32_e32 v102, 16, v102
	v_mul_f32_e32 v102, 0xbfb8aa3b, v102
	v_lshlrev_b32_e32 v65, 16, v65
	v_add_f32_e32 v173, 1.0, v173
	v_mul_f32_e32 v125, v125, v220
	v_exp_f32_e32 v102, v102
	v_mul_f32_e32 v65, 0xbfb8aa3b, v65
	v_rcp_f32_e32 v104, v173
	v_mul_f32_e32 v173, v125, v231
	v_add_f32_e32 v125, 1.0, v184
	v_exp_f32_e32 v184, v65
	v_lshlrev_b32_e32 v63, 16, v63
	v_mul_f32_e32 v63, 0xbfb8aa3b, v63
	v_lshlrev_b32_e32 v64, 16, v64
	v_add_f32_e32 v102, 1.0, v102
	v_mul_f32_e32 v65, v164, v220
	v_exp_f32_e32 v164, v63
	v_mul_f32_e32 v64, 0xbfb8aa3b, v64
	v_mul_f32_e32 v149, v210, v216
	v_rcp_f32_e32 v210, v125
	v_mul_f32_e32 v125, v145, v220
	v_rcp_f32_e32 v145, v102
	v_add_f32_e32 v102, 1.0, v184
	v_exp_f32_e32 v184, v64
	v_lshlrev_b32_e32 v62, 16, v62
	v_mul_f32_e32 v62, 0xbfb8aa3b, v62
	v_lshlrev_b32_e32 v60, 16, v60
	v_add_f32_e32 v164, 1.0, v164
	v_exp_f32_e32 v62, v62
	v_mul_f32_e32 v60, 0xbfb8aa3b, v60
	v_rcp_f32_e32 v64, v164
	v_add_f32_e32 v164, 1.0, v184
	v_exp_f32_e32 v184, v60
	v_lshlrev_b32_e32 v59, 16, v59
	v_mul_f32_e32 v59, 0xbfb8aa3b, v59
	v_lshlrev_b32_e32 v57, 16, v57
	v_add_f32_e32 v62, 1.0, v62
	v_mul_f32_e32 v60, v156, v217
	v_exp_f32_e32 v156, v59
	v_mul_f32_e32 v57, 0xbfb8aa3b, v57
	v_mul_f32_e32 v159, v212, v215
	v_rcp_f32_e32 v212, v62
	v_add_f32_e32 v62, 1.0, v184
	v_exp_f32_e32 v184, v57
	v_lshlrev_b32_e32 v52, 16, v52
	v_lshlrev_b32_e32 v55, 16, v55
	v_lshlrev_b32_e32 v53, 16, v53
	v_mul_f32_e32 v52, 0xbfb8aa3b, v52
	v_lshlrev_b32_e32 v50, 16, v50
	s_waitcnt vmcnt(2)
	v_mul_f32_e32 v229, 0x3f4ccccd, v235
	v_add_f32_e32 v156, 1.0, v156
	v_mul_f32_e32 v55, 0xbfb8aa3b, v55
	v_mul_f32_e32 v53, 0xbfb8aa3b, v53
	v_exp_f32_e32 v52, v52
	v_mul_f32_e32 v118, v118, v213
	v_mul_f32_e32 v50, 0xbfb8aa3b, v50
	v_rcp_f32_e32 v57, v156
	v_mul_f32_e32 v107, v107, v214
	v_add_f32_e32 v156, 1.0, v184
	v_mul_f32_e32 v127, v127, v214
	v_exp_f32_e32 v184, v55
	v_mul_f32_e32 v55, v146, v214
	v_exp_f32_e32 v146, v53
	v_mul_f32_e32 v53, v170, v214
	v_mul_f32_e32 v214, v118, v229
	v_exp_f32_e32 v118, v50
	v_lshlrev_b32_e32 v49, 16, v49
	v_add_f32_e32 v52, 1.0, v52
	v_mul_f32_e32 v49, 0xbfb8aa3b, v49
	v_lshlrev_b32_e32 v48, 16, v48
	v_rcp_f32_e32 v216, v52
	v_add_f32_e32 v52, 1.0, v118
	v_exp_f32_e32 v118, v49
	v_mul_f32_e32 v48, 0xbfb8aa3b, v48
	v_mul_f32_e32 v50, v136, v213
	v_exp_f32_e32 v136, v48
	v_lshlrev_b32_e32 v47, 16, v47
	v_add_f32_e32 v118, 1.0, v118
	v_mul_f32_e32 v47, 0xbfb8aa3b, v47
	v_lshlrev_b32_e32 v45, 16, v45
	v_rcp_f32_e32 v48, v118
	v_add_f32_e32 v118, 1.0, v136
	v_exp_f32_e32 v47, v47
	v_mul_f32_e32 v45, 0xbfb8aa3b, v45
	v_rcp_f32_e32 v136, v118
	v_exp_f32_e32 v118, v45
	v_lshlrev_b32_e32 v43, 16, v43
	v_add_f32_e32 v47, 1.0, v47
	v_mul_f32_e32 v43, 0xbfb8aa3b, v43
	v_lshlrev_b32_e32 v44, 16, v44
	v_mul_f32_e32 v101, v101, v213
	v_mul_f32_e32 v49, v160, v213
	v_rcp_f32_e32 v213, v47
	v_add_f32_e32 v47, 1.0, v118
	v_exp_f32_e32 v118, v43
	v_mul_f32_e32 v44, 0xbfb8aa3b, v44
	v_mul_f32_e32 v45, v128, v232
	v_exp_f32_e32 v128, v44
	v_add_f32_e32 v118, 1.0, v118
	v_lshlrev_b32_e32 v41, 16, v41
	v_rcp_f32_e32 v44, v118
	v_add_f32_e32 v118, 1.0, v128
	v_mul_f32_e32 v41, 0xbfb8aa3b, v41
	v_lshlrev_b32_e32 v40, 16, v40
	v_rcp_f32_e32 v128, v118
	v_exp_f32_e32 v118, v41
	v_mul_f32_e32 v40, 0xbfb8aa3b, v40
	v_mul_f32_e32 v41, v119, v230
	v_exp_f32_e32 v119, v40
	v_lshlrev_b32_e32 v39, 16, v39
	v_add_f32_e32 v118, 1.0, v118
	v_mul_f32_e32 v39, 0xbfb8aa3b, v39
	v_mul_f32_e32 v43, v153, v232
	v_rcp_f32_e32 v153, v118
	v_add_f32_e32 v118, 1.0, v119
	v_exp_f32_e32 v119, v39
	v_lshlrev_b32_e32 v37, 16, v37
	v_rcp_f32_e32 v39, v118
	v_mul_f32_e32 v37, 0xbfb8aa3b, v37
	v_add_f32_e32 v118, 1.0, v119
	v_lshlrev_b32_e32 v36, 16, v36
	s_waitcnt vmcnt(1)
	v_mul_f32_e32 v228, 0x3f4ccccd, v236
	v_lshlrev_b32_e32 v56, 16, v56
	v_mul_f32_e32 v40, v142, v230
	v_rcp_f32_e32 v142, v118
	v_exp_f32_e32 v37, v37
	v_mul_f32_e32 v112, v112, v226
	v_mul_f32_e32 v36, 0xbfb8aa3b, v36
	s_barrier
	ds_read2st64_b32 v[118:119], v68 offset1:1
	v_mul_f32_e32 v116, v116, v217
	v_mul_f32_e32 v135, v135, v217
	v_mul_f32_e32 v59, v185, v217
	v_mul_f32_e32 v56, 0xbfb8aa3b, v56
	v_mul_f32_e32 v217, v228, v112
	v_exp_f32_e32 v112, v36
	v_exp_f32_e32 v56, v56
	v_add_f32_e32 v37, 1.0, v37
	v_rcp_f32_e32 v218, v37
	v_add_f32_e32 v37, 1.0, v112
	s_waitcnt lgkmcnt(0)
	v_fma_f32 v112, v211, v198, v118
	v_add_f32_e32 v56, 1.0, v56
	v_bfe_u32 v118, v112, 16, 1
	v_mul_f32_e32 v105, v193, v224
	v_mul_f32_e32 v63, v189, v220
	v_rcp_f32_e32 v215, v56
	v_add_f32_e32 v56, 1.0, v184
	ds_read2st64_b32 v[184:185], v68 offset0:2 offset1:3
	ds_read2st64_b32 v[188:189], v68 offset0:4 offset1:5
	ds_read2st64_b32 v[192:193], v68 offset0:6 offset1:7
	v_add3_u32 v112, v112, v118, s66
	v_fmac_f32_e32 v119, v202, v194
	global_store_short_d16_hi v35, v112, s[24:25]
	v_bfe_u32 v112, v119, 16, 1
	v_add3_u32 v112, v119, v112, s66
	v_add_u32_e32 v118, 0x800, v35
	global_store_short_d16_hi v118, v112, s[24:25]
	s_waitcnt lgkmcnt(2)
	v_fma_f32 v112, v207, v199, v184
	v_bfe_u32 v118, v112, 16, 1
	v_add3_u32 v112, v112, v118, s66
	v_add_u32_e32 v118, 0x1000, v35
	v_fmac_f32_e32 v185, v205, v195
	global_store_short_d16_hi v118, v112, s[24:25]
	v_bfe_u32 v112, v185, 16, 1
	v_add3_u32 v112, v185, v112, s66
	v_add_u32_e32 v118, 0x1800, v35
	global_store_short_d16_hi v118, v112, s[24:25]
	s_waitcnt lgkmcnt(1)
; __device__ __forceinline__ void attn_unit_pp(int b, int h, int qb, int par, const bf16_t* __restrict__ QBp, const bf16_t* __restrict__ KBp, const bf16_t* __restrict__ VBp, ...
;     ...
; #pragma unroll
;     for (int d0 = 0; d0 < 4; ++d0)
; #pragma unroll
;       for (int r = 0; r < 16; ++r) { const int ro = (r & 3) + 8 * (r >> 2);
;         const float val = o[d0][r] + pgs[(d0 * 16 + r) * 64];
;         unsigned u = __float_as_uint(val); u = (u + 0x7fffu + ((u >> 16) & 1u)) >> 16;
;         MIX_ST(ro, d0 * 32, (unsigned short)u); }
	v_fma_f32 v112, v201, v191, v188
	v_bfe_u32 v118, v112, 16, 1
	v_add3_u32 v112, v112, v118, s66
	v_add_u32_e32 v118, 0x4000, v35
	v_fmac_f32_e32 v189, v204, v197
	global_store_short_d16_hi v118, v112, s[24:25]
	v_bfe_u32 v112, v189, 16, 1
	v_add3_u32 v112, v189, v112, s66
	v_add_u32_e32 v118, 0x4800, v35
	global_store_short_d16_hi v118, v112, s[24:25]
	s_waitcnt lgkmcnt(0)
	v_fma_f32 v112, v203, v206, v192
	v_bfe_u32 v118, v112, 16, 1
	v_add3_u32 v112, v112, v118, s66
	v_add_u32_e32 v118, 0x5000, v35
	global_store_short_d16_hi v118, v112, s[24:25]
	ds_read2st64_b32 v[118:119], v68 offset0:8 offset1:9
	v_lshlrev_b32_e32 v54, 16, v54
	v_fmac_f32_e32 v193, v208, v200
	v_mul_f32_e32 v54, 0xbfb8aa3b, v54
	v_bfe_u32 v112, v193, 16, 1
	v_exp_f32_e32 v170, v54
	v_mul_f32_e32 v36, v144, v226
	v_add3_u32 v112, v193, v112, s66
	v_add_u32_e32 v144, 0x5800, v35
	global_store_short_d16_hi v144, v112, s[24:25]
	s_waitcnt lgkmcnt(0)
	v_fma_f32 v112, v209, v196, v118
	v_rcp_f32_e32 v164, v164
	v_bfe_u32 v118, v112, 16, 1
	v_rcp_f32_e32 v156, v156
	v_add_f32_e32 v146, 1.0, v146
	ds_read2st64_b32 v[184:185], v68 offset0:10 offset1:11
	ds_read2st64_b32 v[188:189], v68 offset0:12 offset1:13
	ds_read2st64_b32 v[192:193], v68 offset0:14 offset1:15
	v_add3_u32 v112, v112, v118, s66
	v_add_u32_e32 v118, 0x8000, v35
	v_fmac_f32_e32 v119, v210, v173
	v_rcp_f32_e32 v54, v146
	v_add_f32_e32 v146, 1.0, v170
	global_store_short_d16_hi v118, v112, s[24:25]
	v_bfe_u32 v112, v119, 16, 1
	v_mul_f32_e32 v116, v116, v231
	v_rcp_f32_e32 v146, v146
	v_add3_u32 v112, v119, v112, s66
	v_add_u32_e32 v118, 0x8800, v35
	v_mul_f32_e32 v107, v107, v231
	global_store_short_d16_hi v118, v112, s[24:25]
	s_waitcnt lgkmcnt(2)
	v_fma_f32 v112, v164, v116, v184
	v_bfe_u32 v116, v112, 16, 1
	v_fmac_f32_e32 v185, v156, v107
	v_mul_f32_e32 v101, v101, v231
	v_mul_f32_e32 v58, v58, v232
	v_add3_u32 v112, v112, v116, s66
	v_add_u32_e32 v116, 0x9000, v35
	v_bfe_u32 v107, v185, 16, 1
	v_mul_f32_e32 v58, v58, v231
	global_store_short_d16_hi v116, v112, s[24:25]
	v_add3_u32 v107, v185, v107, s66
	v_add_u32_e32 v112, 0x9800, v35
	s_waitcnt lgkmcnt(1)
	v_fma_f32 v101, v146, v101, v188
	v_mul_f32_e32 v51, v51, v230
	global_store_short_d16_hi v112, v107, s[24:25]
	v_bfe_u32 v107, v101, 16, 1
	v_fmac_f32_e32 v189, v136, v58
	v_mul_f32_e32 v51, v51, v231
	v_mul_f32_e32 v46, v46, v226
	v_add3_u32 v101, v101, v107, s66
	v_add_u32_e32 v107, 0xc000, v35
	v_bfe_u32 v58, v189, 16, 1
	ds_read2st64_b32 v[118:119], v68 offset0:16 offset1:17
	v_mul_f32_e32 v46, v231, v46
	global_store_short_d16_hi v107, v101, s[24:25]
	v_add3_u32 v58, v189, v58, s66
	v_add_u32_e32 v101, 0xc800, v35
	s_waitcnt lgkmcnt(1)
	v_fma_f32 v51, v128, v51, v192
	global_store_short_d16_hi v101, v58, s[24:25]
	v_bfe_u32 v58, v51, 16, 1
	v_fmac_f32_e32 v193, v142, v46
	v_add3_u32 v51, v51, v58, s66
	v_add_u32_e32 v58, 0xd000, v35
	v_bfe_u32 v46, v193, 16, 1
	v_mul_f32_e32 v165, v165, v229
	global_store_short_d16_hi v58, v51, s[24:25]
	v_add3_u32 v46, v193, v46, s66
	v_add_u32_e32 v51, 0xd800, v35
	global_store_short_d16_hi v51, v46, s[24:25]
	s_waitcnt lgkmcnt(0)
	v_fma_f32 v51, v169, v165, v118
	v_mul_f32_e32 v180, v180, v229
	v_bfe_u32 v58, v51, 16, 1
	v_add_u32_e32 v46, 64, v35
	ds_read2st64_b32 v[184:185], v68 offset0:18 offset1:19
	ds_read2st64_b32 v[188:189], v68 offset0:20 offset1:21
	ds_read2st64_b32 v[192:193], v68 offset0:22 offset1:23
	v_add3_u32 v51, v51, v58, s66
	v_fmac_f32_e32 v119, v181, v180
	global_store_short_d16_hi v46, v51, s[24:25]
	v_bfe_u32 v46, v119, 16, 1
	v_mul_f32_e32 v182, v182, v229
	v_add3_u32 v46, v119, v46, s66
	v_add_u32_e32 v51, 0x840, v35
	global_store_short_d16_hi v51, v46, s[24:25]
	s_waitcnt lgkmcnt(2)
	v_fma_f32 v46, v183, v182, v184
	v_mul_f32_e32 v186, v186, v229
	v_bfe_u32 v51, v46, 16, 1
	v_add3_u32 v46, v46, v51, s66
	v_add_u32_e32 v51, 0x1040, v35
	v_fmac_f32_e32 v185, v190, v186
	global_store_short_d16_hi v51, v46, s[24:25]
	v_bfe_u32 v46, v185, 16, 1
	v_mul_f32_e32 v171, v171, v229
	v_add3_u32 v46, v185, v46, s66
	v_add_u32_e32 v51, 0x1840, v35
	global_store_short_d16_hi v51, v46, s[24:25]
	s_waitcnt lgkmcnt(1)
	v_fma_f32 v46, v187, v171, v188
	v_mul_f32_e32 v161, v161, v229
	v_bfe_u32 v51, v46, 16, 1
	v_add3_u32 v46, v46, v51, s66
	v_add_u32_e32 v51, 0x4040, v35
	v_fmac_f32_e32 v189, v172, v161
	global_store_short_d16_hi v51, v46, s[24:25]
	v_bfe_u32 v46, v189, 16, 1
	v_mul_f32_e32 v150, v150, v229
	v_add3_u32 v46, v189, v46, s66
	v_add_u32_e32 v51, 0x4840, v35
	global_store_short_d16_hi v51, v46, s[24:25]
	s_waitcnt lgkmcnt(0)
	v_fma_f32 v46, v167, v150, v192
	ds_read2st64_b32 v[118:119], v68 offset0:24 offset1:25
	v_mul_f32_e32 v140, v140, v229
	v_bfe_u32 v51, v46, 16, 1
	v_add3_u32 v46, v46, v51, s66
	v_add_u32_e32 v51, 0x5040, v35
	v_fmac_f32_e32 v193, v158, v140
	global_store_short_d16_hi v51, v46, s[24:25]
	v_bfe_u32 v46, v193, 16, 1
	v_mul_f32_e32 v132, v132, v229
	v_add3_u32 v46, v193, v46, s66
	v_add_u32_e32 v51, 0x5840, v35
	global_store_short_d16_hi v51, v46, s[24:25]
	s_waitcnt lgkmcnt(0)
	v_fma_f32 v46, v155, v132, v118
	v_mul_f32_e32 v125, v125, v229
	v_bfe_u32 v51, v46, 16, 1
	ds_read2st64_b32 v[160:161], v68 offset0:26 offset1:27
	ds_read2st64_b32 v[164:165], v68 offset0:28 offset1:29
	ds_read2st64_b32 v[170:171], v68 offset0:30 offset1:31
	v_add3_u32 v46, v46, v51, s66
	v_add_u32_e32 v51, 0x8040, v35
	v_fmac_f32_e32 v119, v145, v125
	v_lshlrev_b32_e32 v42, 16, v42
	global_store_short_d16_hi v51, v46, s[24:25]
	v_bfe_u32 v46, v119, 16, 1
	v_mul_f32_e32 v135, v135, v229
	v_mul_f32_e32 v42, 0xbfb8aa3b, v42
	v_lshlrev_b32_e32 v38, 16, v38
	v_add3_u32 v46, v119, v46, s66
	v_add_u32_e32 v51, 0x8840, v35
	v_exp_f32_e32 v42, v42
	v_mul_f32_e32 v38, 0xbfb8aa3b, v38
	global_store_short_d16_hi v51, v46, s[24:25]
	s_waitcnt lgkmcnt(2)
; __device__ __forceinline__ void attn_unit_pp(int b, int h, int qb, int par, const bf16_t* __restrict__ QBp, const bf16_t* __restrict__ KBp, const bf16_t* __restrict__ VBp, ...
;     ...
; #pragma unroll
;     for (int d0 = 0; d0 < 4; ++d0)
; #pragma unroll
;       for (int r = 0; r < 16; ++r) { const int ro = (r & 3) + 8 * (r >> 2);
;         const float val = o[d0][r] + pgs[(d0 * 16 + r) * 64];
;         unsigned u = __float_as_uint(val); u = (u + 0x7fffu + ((u >> 16) & 1u)) >> 16;
;         MIX_ST(ro, d0 * 32, (unsigned short)u); }
	v_fma_f32 v46, v212, v135, v160
	v_mul_f32_e32 v127, v127, v229
	v_exp_f32_e32 v38, v38
	v_bfe_u32 v51, v46, 16, 1
	v_add3_u32 v46, v46, v51, s66
	v_add_u32_e32 v51, 0x9040, v35
	v_fmac_f32_e32 v161, v215, v127
	global_store_short_d16_hi v51, v46, s[24:25]
	v_bfe_u32 v46, v161, 16, 1
	v_add_f32_e32 v42, 1.0, v42
	v_add3_u32 v46, v161, v46, s66
	v_add_u32_e32 v51, 0x9840, v35
	v_mul_f32_e32 v111, v111, v232
	v_rcp_f32_e32 v42, v42
	v_add_f32_e32 v38, 1.0, v38
	global_store_short_d16_hi v51, v46, s[24:25]
	s_waitcnt lgkmcnt(1)
	v_fma_f32 v46, v216, v214, v164
	v_mul_f32_e32 v111, v111, v229
	v_rcp_f32_e32 v38, v38
	v_bfe_u32 v51, v46, 16, 1
	v_mul_f32_e32 v103, v103, v230
	v_add3_u32 v46, v46, v51, s66
	v_add_u32_e32 v51, 0xc040, v35
	v_fmac_f32_e32 v165, v213, v111
	v_mul_f32_e32 v103, v103, v229
	v_mul_f32_e32 v61, v61, v226
	global_store_short_d16_hi v51, v46, s[24:25]
	v_bfe_u32 v46, v165, 16, 1
	ds_read2st64_b32 v[118:119], v68 offset0:32 offset1:33
	v_rcp_f32_e32 v163, v163
	v_mul_f32_e32 v61, v229, v61
	v_add3_u32 v46, v165, v46, s66
	v_add_u32_e32 v51, 0xc840, v35
	s_waitcnt lgkmcnt(1)
	v_fma_f32 v42, v42, v103, v170
	global_store_short_d16_hi v51, v46, s[24:25]
	v_bfe_u32 v46, v42, 16, 1
	v_fmac_f32_e32 v171, v38, v61
	v_rcp_f32_e32 v154, v154
	v_add3_u32 v42, v42, v46, s66
	v_add_u32_e32 v46, 0xd040, v35
	v_bfe_u32 v38, v171, 16, 1
	v_mul_f32_e32 v162, v162, v228
	global_store_short_d16_hi v46, v42, s[24:25]
	v_add3_u32 v38, v171, v38, s66
	v_add_u32_e32 v42, 0xd840, v35
	global_store_short_d16_hi v42, v38, s[24:25]
	s_waitcnt lgkmcnt(0)
	v_fma_f32 v42, v163, v162, v118
	v_mul_f32_e32 v152, v152, v228
	v_rcp_f32_e32 v148, v148
	v_bfe_u32 v46, v42, 16, 1
	v_add_u32_e32 v38, 0x80, v35
	ds_read2st64_b32 v[144:145], v68 offset0:34 offset1:35
	ds_read2st64_b32 v[160:161], v68 offset0:36 offset1:37
	ds_read2st64_b32 v[164:165], v68 offset0:38 offset1:39
	v_add3_u32 v42, v42, v46, s66
	v_fmac_f32_e32 v119, v154, v152
	v_rcp_f32_e32 v139, v139
	global_store_short_d16_hi v38, v42, s[24:25]
	v_bfe_u32 v38, v119, 16, 1
	v_mul_f32_e32 v147, v147, v228
	v_add3_u32 v38, v119, v38, s66
	v_add_u32_e32 v42, 0x880, v35
	global_store_short_d16_hi v42, v38, s[24:25]
	s_waitcnt lgkmcnt(2)
	v_fma_f32 v38, v148, v147, v144
	v_mul_f32_e32 v138, v138, v228
	v_rcp_f32_e32 v133, v133
	v_bfe_u32 v42, v38, 16, 1
	v_add3_u32 v38, v38, v42, s66
	v_add_u32_e32 v42, 0x1080, v35
	v_fmac_f32_e32 v145, v139, v138
	v_rcp_f32_e32 v126, v126
	global_store_short_d16_hi v42, v38, s[24:25]
	v_bfe_u32 v38, v145, 16, 1
	v_mul_f32_e32 v131, v131, v228
	v_add3_u32 v38, v145, v38, s66
	v_add_u32_e32 v42, 0x1880, v35
	global_store_short_d16_hi v42, v38, s[24:25]
	s_waitcnt lgkmcnt(1)
	v_fma_f32 v38, v133, v131, v160
	v_mul_f32_e32 v124, v124, v228
	v_rcp_f32_e32 v121, v121
	v_rcp_f32_e32 v114, v114
	v_bfe_u32 v42, v38, 16, 1
	v_add3_u32 v38, v38, v42, s66
	v_add_u32_e32 v42, 0x4080, v35
	v_fmac_f32_e32 v161, v126, v124
	global_store_short_d16_hi v42, v38, s[24:25]
	v_bfe_u32 v38, v161, 16, 1
	v_mul_f32_e32 v120, v120, v228
	v_mul_f32_e32 v113, v113, v228
	v_add3_u32 v38, v161, v38, s66
	v_add_u32_e32 v42, 0x4880, v35
	global_store_short_d16_hi v42, v38, s[24:25]
	s_waitcnt lgkmcnt(0)
	v_fma_f32 v38, v121, v120, v164
	v_fmac_f32_e32 v165, v114, v113
	ds_read2st64_b32 v[112:113], v68 offset0:40 offset1:41
	v_rcp_f32_e32 v108, v108
	v_bfe_u32 v42, v38, 16, 1
	v_add3_u32 v38, v38, v42, s66
	v_add_u32_e32 v42, 0x5080, v35
	v_rcp_f32_e32 v102, v102
	global_store_short_d16_hi v42, v38, s[24:25]
	v_bfe_u32 v38, v165, 16, 1
	v_mul_f32_e32 v106, v106, v228
	v_add3_u32 v38, v165, v38, s66
	v_add_u32_e32 v42, 0x5880, v35
	global_store_short_d16_hi v42, v38, s[24:25]
	s_waitcnt lgkmcnt(0)
	v_fma_f32 v38, v108, v106, v112
	v_mul_f32_e32 v65, v65, v228
	v_rcp_f32_e32 v62, v62
	v_bfe_u32 v42, v38, 16, 1
	ds_read2st64_b32 v[118:119], v68 offset0:42 offset1:43
	ds_read2st64_b32 v[120:121], v68 offset0:44 offset1:45
	ds_read2st64_b32 v[124:125], v68 offset0:46 offset1:47
	v_add3_u32 v38, v38, v42, s66
	v_add_u32_e32 v42, 0x8080, v35
	v_fmac_f32_e32 v113, v102, v65
	v_rcp_f32_e32 v56, v56
	global_store_short_d16_hi v42, v38, s[24:25]
	v_bfe_u32 v38, v113, 16, 1
	v_mul_f32_e32 v60, v60, v228
	v_add3_u32 v38, v113, v38, s66
	v_add_u32_e32 v42, 0x8880, v35
	global_store_short_d16_hi v42, v38, s[24:25]
	s_waitcnt lgkmcnt(2)
	v_fma_f32 v38, v62, v60, v118
	v_mul_f32_e32 v55, v55, v228
	v_rcp_f32_e32 v52, v52
	v_bfe_u32 v42, v38, 16, 1
	v_add3_u32 v38, v38, v42, s66
	v_add_u32_e32 v42, 0x9080, v35
	v_fmac_f32_e32 v119, v56, v55
	v_rcp_f32_e32 v47, v47
	global_store_short_d16_hi v42, v38, s[24:25]
	v_bfe_u32 v38, v119, 16, 1
	v_mul_f32_e32 v50, v50, v228
	v_add3_u32 v38, v119, v38, s66
	v_add_u32_e32 v42, 0x9880, v35
	global_store_short_d16_hi v42, v38, s[24:25]
	s_waitcnt lgkmcnt(1)
	v_fma_f32 v38, v52, v50, v120
	v_mul_f32_e32 v45, v45, v228
	v_bfe_u32 v42, v38, 16, 1
	v_add3_u32 v38, v38, v42, s66
	v_add_u32_e32 v42, 0xc080, v35
	v_fmac_f32_e32 v121, v47, v45
	global_store_short_d16_hi v42, v38, s[24:25]
	v_bfe_u32 v38, v121, 16, 1
	v_mul_f32_e32 v41, v41, v228
	v_add3_u32 v38, v121, v38, s66
	v_add_u32_e32 v42, 0xc880, v35
	global_store_short_d16_hi v42, v38, s[24:25]
	s_waitcnt lgkmcnt(0)
	v_fma_f32 v38, v153, v41, v124
	ds_read2st64_b32 v[46:47], v68 offset0:48 offset1:49
	v_bfe_u32 v41, v38, 16, 1
	v_add3_u32 v38, v38, v41, s66
	v_add_u32_e32 v41, 0xd080, v35
	v_fmac_f32_e32 v125, v218, v217
	s_waitcnt vmcnt(46)
	v_mul_f32_e32 v227, 0x3f4ccccd, v237
	global_store_short_d16_hi v41, v38, s[24:25]
	v_bfe_u32 v38, v125, 16, 1
	v_mul_f32_e32 v159, v159, v227
	v_add3_u32 v38, v125, v38, s66
	v_add_u32_e32 v41, 0xd880, v35
	global_store_short_d16_hi v41, v38, s[24:25]
	s_waitcnt lgkmcnt(0)
; __device__ __forceinline__ float sigm_(float x) { return __builtin_amdgcn_rcpf(1.0f + __builtin_amdgcn_exp2f(-1.4426950408889634f * x)); }
; __device__ __forceinline__ void attn_unit_pp(int b, int h, int qb, int par, const bf16_t* __restrict__ QBp, const bf16_t* __restrict__ KBp, const bf16_t* __restrict__ VBp, ...
;     ...
;   if (g == 1) {
;     unsigned gate16[64];
; #pragma unroll
;     for (int r = 0; r < 16; ++r)
; #pragma unroll
;       for (int d0 = 0; d0 < 4; ++d0) gate16[r * 4 + d0] = GATE_LD((r & 3) + 8 * (r >> 2), 1024 + d0 * 32);
;     ...
;     for (int d0 = 0; d0 < 4; ++d0) sg[d0] = sub_g[d0 * 32 + r32] * 0.8f;
; #pragma unroll
;     for (int r = 0; r < 16; ++r)
; #pragma unroll
;       for (int d0 = 0; d0 < 4; ++d0) { const float ga = __uint_as_float(gate16[r * 4 + d0] << 16); o[d0][r] = o[d0][r] * ss[r] * sg[d0] * sigm_(ga); }
;     __syncthreads();
; #pragma unroll
;     for (int d0 = 0; d0 < 4; ++d0)
; #pragma unroll
;       for (int r = 0; r < 16; ++r) { const int ro = (r & 3) + 8 * (r >> 2);
;         const float val = o[d0][r] + pgs[(d0 * 16 + r) * 64];
;         unsigned u = __float_as_uint(val); u = (u + 0x7fffu + ((u >> 16) & 1u)) >> 16;
;         MIX_ST(ro, d0 * 32, (unsigned short)u); }
	v_fma_f32 v41, v157, v159, v46
	v_mul_f32_e32 v149, v149, v227
	v_bfe_u32 v42, v41, 16, 1
	v_add_u32_e32 v38, 0xc0, v35
	ds_read2st64_b32 v[50:51], v68 offset0:50 offset1:51
	ds_read2st64_b32 v[60:61], v68 offset0:52 offset1:53
	ds_read2st64_b32 v[102:103], v68 offset0:54 offset1:55
	v_add3_u32 v41, v41, v42, s66
	v_fmac_f32_e32 v47, v151, v149
	global_store_short_d16_hi v38, v41, s[24:25]
	v_bfe_u32 v38, v47, 16, 1
	v_mul_f32_e32 v143, v143, v227
	v_add3_u32 v38, v47, v38, s66
	v_add_u32_e32 v41, 0x8c0, v35
	global_store_short_d16_hi v41, v38, s[24:25]
	s_waitcnt lgkmcnt(2)
	v_fma_f32 v38, v141, v143, v50
	v_mul_f32_e32 v134, v134, v227
	v_bfe_u32 v41, v38, 16, 1
	v_add3_u32 v38, v38, v41, s66
	v_add_u32_e32 v41, 0x10c0, v35
	v_fmac_f32_e32 v51, v137, v134
	global_store_short_d16_hi v41, v38, s[24:25]
	v_bfe_u32 v38, v51, 16, 1
	v_mul_f32_e32 v130, v130, v227
	v_add3_u32 v38, v51, v38, s66
	v_add_u32_e32 v41, 0x18c0, v35
	global_store_short_d16_hi v41, v38, s[24:25]
	s_waitcnt lgkmcnt(1)
	v_fma_f32 v38, v129, v130, v60
	v_mul_f32_e32 v122, v122, v227
	v_bfe_u32 v41, v38, 16, 1
	v_add3_u32 v38, v38, v41, s66
	v_add_u32_e32 v41, 0x40c0, v35
	v_fmac_f32_e32 v61, v123, v122
	global_store_short_d16_hi v41, v38, s[24:25]
	v_bfe_u32 v38, v61, 16, 1
	v_mul_f32_e32 v117, v117, v227
	v_add3_u32 v38, v61, v38, s66
	v_add_u32_e32 v41, 0x48c0, v35
	global_store_short_d16_hi v41, v38, s[24:25]
	s_waitcnt lgkmcnt(0)
	v_fma_f32 v38, v115, v117, v102
	ds_read2st64_b32 v[46:47], v68 offset0:56 offset1:57
	v_mul_f32_e32 v109, v109, v227
	v_bfe_u32 v41, v38, 16, 1
	v_add3_u32 v38, v38, v41, s66
	v_add_u32_e32 v41, 0x50c0, v35
	v_fmac_f32_e32 v103, v110, v109
	global_store_short_d16_hi v41, v38, s[24:25]
	v_bfe_u32 v38, v103, 16, 1
	v_mul_f32_e32 v105, v105, v227
	v_add3_u32 v38, v103, v38, s66
	v_add_u32_e32 v41, 0x58c0, v35
	global_store_short_d16_hi v41, v38, s[24:25]
	s_waitcnt lgkmcnt(0)
	v_fma_f32 v38, v104, v105, v46
	v_mul_f32_e32 v63, v63, v227
	v_bfe_u32 v41, v38, 16, 1
	ds_read2st64_b32 v[50:51], v68 offset0:58 offset1:59
	ds_read2st64_b32 v[60:61], v68 offset0:60 offset1:61
	ds_read2st64_b32 v[102:103], v68 offset0:62 offset1:63
	v_add3_u32 v38, v38, v41, s66
	v_add_u32_e32 v41, 0x80c0, v35
	v_fmac_f32_e32 v47, v64, v63
	global_store_short_d16_hi v41, v38, s[24:25]
	v_bfe_u32 v38, v47, 16, 1
	v_mul_f32_e32 v59, v59, v227
	v_add3_u32 v38, v47, v38, s66
	v_add_u32_e32 v41, 0x88c0, v35
	global_store_short_d16_hi v41, v38, s[24:25]
	s_waitcnt lgkmcnt(2)
	v_fma_f32 v38, v57, v59, v50
	v_mul_f32_e32 v53, v53, v227
	v_bfe_u32 v41, v38, 16, 1
	v_add3_u32 v38, v38, v41, s66
	v_add_u32_e32 v41, 0x90c0, v35
	v_fmac_f32_e32 v51, v54, v53
	global_store_short_d16_hi v41, v38, s[24:25]
	v_bfe_u32 v38, v51, 16, 1
	v_mul_f32_e32 v49, v49, v227
	v_add3_u32 v38, v51, v38, s66
	v_add_u32_e32 v41, 0x98c0, v35
	global_store_short_d16_hi v41, v38, s[24:25]
	s_waitcnt lgkmcnt(1)
	v_fma_f32 v38, v48, v49, v60
	v_mul_f32_e32 v43, v43, v227
	v_rcp_f32_e32 v37, v37
	v_bfe_u32 v41, v38, 16, 1
	v_add3_u32 v38, v38, v41, s66
	v_add_u32_e32 v41, 0xc0c0, v35
	v_fmac_f32_e32 v61, v44, v43
	global_store_short_d16_hi v41, v38, s[24:25]
	v_bfe_u32 v38, v61, 16, 1
	v_mul_f32_e32 v40, v40, v227
	v_mul_f32_e32 v36, v227, v36
	v_add3_u32 v38, v61, v38, s66
	v_add_u32_e32 v41, 0xc8c0, v35
	global_store_short_d16_hi v41, v38, s[24:25]
	s_waitcnt lgkmcnt(0)
	v_fma_f32 v38, v39, v40, v102
	v_fmac_f32_e32 v103, v37, v36
	v_bfe_u32 v39, v38, 16, 1
	v_bfe_u32 v36, v103, 16, 1
	v_add3_u32 v38, v38, v39, s66
	v_add_u32_e32 v39, 0xd0c0, v35
	v_add3_u32 v36, v103, v36, s66
	v_add_u32_e32 v35, 0xd8c0, v35
	global_store_short_d16_hi v39, v38, s[24:25]
	global_store_short_d16_hi v35, v36, s[24:25]
	s_cbranch_execnz .LBB0_338
.LBB0_412:
	v_add_u32_e32 v35, 0x800, v34
	v_add_u32_e32 v36, 0x840, v34
	v_add_u32_e32 v37, 0x880, v34
	v_add_u32_e32 v38, 0x8c0, v34
	v_add_u32_e32 v39, 0x1800, v34
	v_add_u32_e32 v40, 0x1840, v34
	v_add_u32_e32 v41, 0x1880, v34
	v_add_u32_e32 v42, 0x18c0, v34
	global_load_ushort v149, v35, s[20:21] nt
	global_load_ushort v133, v36, s[20:21] nt
	global_load_ushort v122, v37, s[20:21] nt
	global_load_ushort v102, v38, s[20:21] nt
	global_load_ushort v150, v39, s[20:21] nt
	global_load_ushort v134, v40, s[20:21] nt
	global_load_ushort v120, v41, s[20:21] nt
	global_load_ushort v101, v42, s[20:21] nt
	v_add_u32_e32 v35, 0x2800, v34
	v_add_u32_e32 v36, 0x2840, v34
	v_add_u32_e32 v37, 0x2880, v34
	v_add_u32_e32 v38, 0x28c0, v34
	v_add_u32_e32 v39, 0x3800, v34
	v_add_u32_e32 v40, 0x3840, v34
	v_add_u32_e32 v41, 0x3880, v34
	v_add_u32_e32 v42, 0x38c0, v34
	global_load_ushort v151, v35, s[20:21] nt
	global_load_ushort v136, v36, s[20:21] nt
	global_load_ushort v126, v37, s[20:21] nt
	global_load_ushort v104, v38, s[20:21] nt
	global_load_ushort v152, v39, s[20:21] nt
	global_load_ushort v135, v40, s[20:21] nt
	global_load_ushort v125, v41, s[20:21] nt
	global_load_ushort v103, v42, s[20:21] nt
	v_add_u32_e32 v35, 0x8800, v34
	v_add_u32_e32 v36, 0x8840, v34
	v_add_u32_e32 v37, 0x8880, v34
	v_add_u32_e32 v38, 0x88c0, v34
	v_add_u32_e32 v39, 0x9800, v34
	v_add_u32_e32 v40, 0x9840, v34
	v_add_u32_e32 v41, 0x9880, v34
	v_add_u32_e32 v42, 0x98c0, v34
	global_load_ushort v153, v35, s[20:21] nt
	global_load_ushort v138, v36, s[20:21] nt
	global_load_ushort v128, v37, s[20:21] nt
	global_load_ushort v106, v38, s[20:21] nt
	global_load_ushort v154, v39, s[20:21] nt
	global_load_ushort v137, v40, s[20:21] nt
	global_load_ushort v127, v41, s[20:21] nt
	global_load_ushort v105, v42, s[20:21] nt
	v_add_u32_e32 v35, 0xa800, v34
	v_add_u32_e32 v36, 0xa840, v34
	v_add_u32_e32 v37, 0xa880, v34
; __device__ __forceinline__ void attn_unit_pp(int b, int h, int qb, int par, const bf16_t* __restrict__ QBp, const bf16_t* __restrict__ KBp, const bf16_t* __restrict__ VBp, ...
;     ...
;   if (g == 1) {
;     unsigned gate16[64];
; #pragma unroll
;     for (int r = 0; r < 16; ++r)
; #pragma unroll
;       for (int d0 = 0; d0 < 4; ++d0) gate16[r * 4 + d0] = GATE_LD((r & 3) + 8 * (r >> 2), 1024 + d0 * 32);
;     bf16x8 pf[8];
;     { const bf16_t* pr = PLDp + (size_t)(rowbase + q0 + w4 * QBLK + r32) * 512 + (h >> 1) * 128 + hi * 8;
; #pragma unroll
;       for (int ks = 0; ks < 8; ++ks) pf[ks] = ld8(pr + ks * 16); }
; #pragma unroll
;     for (int d0 = 0; d0 < 4; ++d0)
; #pragma unroll
;       for (int r = 0; r < 16; ++r) xs[(d0 * 16 + r) * 64] = o[d0][r];
;     __syncthreads();
	v_add_u32_e32 v38, 0xa8c0, v34
	v_add_u32_e32 v39, 0xb800, v34
	v_add_u32_e32 v40, 0xb840, v34
	v_add_u32_e32 v41, 0xb880, v34
	v_or_b32_e32 v2, v2, v179
	v_add_u32_e32 v42, 0xb8c0, v34
	global_load_ushort v155, v35, s[20:21] nt
	global_load_ushort v140, v36, s[20:21] nt
	global_load_ushort v130, v37, s[20:21] nt
	global_load_ushort v108, v38, s[20:21] nt
	global_load_ushort v156, v39, s[20:21] nt
	global_load_ushort v139, v40, s[20:21] nt
	global_load_ushort v129, v41, s[20:21] nt
	global_load_ushort v107, v42, s[20:21] nt
	v_add_u32_e32 v35, 0x10800, v34
	v_add_u32_e32 v36, 0x10840, v34
	v_add_u32_e32 v37, 0x10880, v34
	v_add_u32_e32 v38, 0x108c0, v34
	v_add_u32_e32 v39, 0x11800, v34
	v_add_u32_e32 v40, 0x11840, v34
	v_add_u32_e32 v41, 0x11880, v34
	v_lshlrev_b64 v[2:3], 10, v[2:3]
	v_add_u32_e32 v42, 0x118c0, v34
	global_load_ushort v157, v35, s[20:21] nt
	global_load_ushort v141, v36, s[20:21] nt
	global_load_ushort v132, v37, s[20:21] nt
	global_load_ushort v110, v38, s[20:21] nt
	global_load_ushort v158, v39, s[20:21] nt
	global_load_ushort v142, v40, s[20:21] nt
	global_load_ushort v131, v41, s[20:21] nt
	global_load_ushort v109, v42, s[20:21] nt
	v_add_u32_e32 v35, 0x12800, v34
	v_add_u32_e32 v36, 0x12840, v34
	v_add_u32_e32 v37, 0x12880, v34
	v_add_u32_e32 v38, 0x128c0, v34
	v_add_u32_e32 v39, 0x13800, v34
	v_add_u32_e32 v40, 0x13840, v34
	v_add_u32_e32 v41, 0x13880, v34
	v_lshl_add_u64 v[2:3], s[56:57], 0, v[2:3]
	s_and_b32 s6, s10, 0x300
	v_add_u32_e32 v42, 0x138c0, v34
	global_load_ushort v159, v35, s[20:21] nt
	global_load_ushort v147, v36, s[20:21] nt
	global_load_ushort v118, v37, s[20:21] nt
	global_load_ushort v112, v38, s[20:21] nt
	global_load_ushort v160, v39, s[20:21] nt
	global_load_ushort v143, v40, s[20:21] nt
	global_load_ushort v117, v41, s[20:21] nt
	global_load_ushort v111, v42, s[20:21] nt
	v_add_u32_e32 v35, 0x18800, v34
	v_add_u32_e32 v36, 0x18840, v34
	v_add_u32_e32 v37, 0x18880, v34
	v_add_u32_e32 v38, 0x188c0, v34
	v_add_u32_e32 v39, 0x19800, v34
	v_add_u32_e32 v40, 0x19840, v34
	v_add_u32_e32 v41, 0x19880, v34
	v_lshl_add_u64 v[2:3], v[2:3], 0, s[6:7]
	v_mov_b32_e32 v169, v1
	s_and_b32 s0, s10, 0x80
	v_add_u32_e32 v42, 0x198c0, v34
	global_load_ushort v161, v35, s[20:21] nt
	global_load_ushort v144, v36, s[20:21] nt
	global_load_ushort v121, v37, s[20:21] nt
	global_load_ushort v114, v38, s[20:21] nt
	global_load_ushort v162, v39, s[20:21] nt
	global_load_ushort v145, v40, s[20:21] nt
	global_load_ushort v119, v41, s[20:21] nt
	global_load_ushort v113, v42, s[20:21] nt
	v_add_u32_e32 v35, 0x1a800, v34
	v_add_u32_e32 v36, 0x1a840, v34
	v_add_u32_e32 v37, 0x1a880, v34
	v_add_u32_e32 v38, 0x1a8c0, v34
	v_add_u32_e32 v39, 0x1b800, v34
	v_add_u32_e32 v40, 0x1b840, v34
	v_add_u32_e32 v41, 0x1b880, v34
	v_add_u32_e32 v34, 0x1b8c0, v34
	v_lshl_add_u64 v[2:3], v[2:3], 0, v[168:169]
	s_or_b32 s0, s6, s0
	global_load_ushort v163, v35, s[20:21] nt
	global_load_ushort v148, v36, s[20:21] nt
	global_load_ushort v123, v37, s[20:21] nt
	global_load_ushort v116, v38, s[20:21] nt
	global_load_ushort v164, v39, s[20:21] nt
	global_load_ushort v146, v40, s[20:21] nt
	global_load_ushort v124, v41, s[20:21] nt
	global_load_ushort v115, v34, s[20:21] nt
	global_load_dwordx4 v[62:65], v[2:3], off
	global_load_dwordx4 v[58:61], v[2:3], off offset:32
	global_load_dwordx4 v[54:57], v[2:3], off offset:64
	global_load_dwordx4 v[50:53], v[2:3], off offset:96
	global_load_dwordx4 v[46:49], v[2:3], off offset:128
	global_load_dwordx4 v[42:45], v[2:3], off offset:160
	global_load_dwordx4 v[38:41], v[2:3], off offset:192
	global_load_dwordx4 v[34:37], v[2:3], off offset:224
	ds_write2st64_b32 v78, v9, v13 offset1:1
	ds_write2st64_b32 v78, v17, v32 offset0:2 offset1:3
	ds_write2st64_b32 v78, v67, v80 offset0:4 offset1:5
	ds_write2st64_b32 v78, v82, v22 offset0:6 offset1:7
	ds_write2st64_b32 v78, v86, v88 offset0:8 offset1:9
	ds_write2st64_b32 v78, v90, v91 offset0:10 offset1:11
	ds_write2st64_b32 v78, v93, v96 offset0:12 offset1:13
	ds_write2st64_b32 v78, v98, v100 offset0:14 offset1:15
	ds_write2st64_b32 v78, v6, v10 offset0:16 offset1:17
	ds_write2st64_b32 v78, v14, v18 offset0:18 offset1:19
	ds_write2st64_b32 v78, v33, v69 offset0:20 offset1:21
	ds_write2st64_b32 v78, v70, v83 offset0:22 offset1:23
	ds_write2st64_b32 v78, v84, v85 offset0:24 offset1:25
	ds_write2st64_b32 v78, v87, v89 offset0:26 offset1:27
	ds_write2st64_b32 v78, v92, v94 offset0:28 offset1:29
	ds_write2st64_b32 v78, v97, v99 offset0:30 offset1:31
	ds_write2st64_b32 v78, v4, v7 offset0:32 offset1:33
	ds_write2st64_b32 v78, v11, v15 offset0:34 offset1:35
	ds_write2st64_b32 v78, v19, v66 offset0:36 offset1:37
	ds_write2st64_b32 v78, v81, v71 offset0:38 offset1:39
	ds_write2st64_b32 v78, v72, v73 offset0:40 offset1:41
	ds_write2st64_b32 v78, v74, v75 offset0:42 offset1:43
	ds_write2st64_b32 v78, v76, v77 offset0:44 offset1:45
	ds_write2st64_b32 v78, v95, v79 offset0:46 offset1:47
	ds_write2st64_b32 v78, v0, v5 offset0:48 offset1:49
	ds_write2st64_b32 v78, v8, v12 offset0:50 offset1:51
	ds_write2st64_b32 v78, v16, v20 offset0:52 offset1:53
	ds_write2st64_b32 v78, v21, v23 offset0:54 offset1:55
	ds_write2st64_b32 v78, v24, v25 offset0:56 offset1:57
	ds_write2st64_b32 v78, v26, v27 offset0:58 offset1:59
	ds_write2st64_b32 v78, v28, v29 offset0:60 offset1:61
	ds_write2st64_b32 v78, v30, v31 offset0:62 offset1:63
	v_or_b32_e32 v0, s0, v179
	v_readlane_b32 s0, v238, 14
	v_lshlrev_b32_e32 v0, 8, v0
	v_readlane_b32 s1, v238, 15
	s_waitcnt lgkmcnt(0)
	s_barrier
; __device__ __forceinline__ float sigm_(float x) { return __builtin_amdgcn_rcpf(1.0f + __builtin_amdgcn_exp2f(-1.4426950408889634f * x)); }
; __device__ __forceinline__ void attn_unit_pp(int b, int h, int qb, int par, const bf16_t* __restrict__ QBp, const bf16_t* __restrict__ KBp, const bf16_t* __restrict__ VBp, ...
;     ...
;     const bf16_t* wpb = WPLp + (size_t)((h >> 1) * 256 + (h & 1) * 128 + r32) * 128 + hi * 8;
; #pragma unroll
;     for (int dp = 0; dp < 2; ++dp) {
;       bf16x8 wp[2][8];
; #pragma unroll
;       for (int e = 0; e < 2; ++e)
; #pragma unroll
;         for (int ks = 0; ks < 8; ++ks) wp[e][ks] = ld8(wpb + (dp * 2 + e) * 32 * 128 + ks * 16);
; #pragma unroll
;       for (int e = 0; e < 2; ++e) { const int d0 = dp * 2 + e; f32x16 acc = f32x16{};
; #pragma unroll
;         for (int ks = 0; ks < 8; ++ks) acc = __builtin_amdgcn_mfma_f32_32x32x16_bf16(pf[ks], wp[e][ks], acc, 0, 0, 0);
; #pragma unroll
;         for (int r = 0; r < 16; ++r) pgs[(d0 * 16 + r) * 64] = sigm_(__uint_as_float(gate16[r * 4 + d0] << 16)) * acc[r]; }
	v_lshl_add_u64 v[2:3], s[0:1], 0, v[0:1]
	v_lshl_add_u64 v[66:67], v[2:3], 0, v[168:169]
	global_load_dwordx4 v[2:5], v[66:67], off
	global_load_dwordx4 v[6:9], v[66:67], off offset:32
	global_load_dwordx4 v[26:29], v[66:67], off offset:64
	global_load_dwordx4 v[30:33], v[66:67], off offset:96
	s_waitcnt vmcnt(3)
	v_mfma_f32_32x32x16_bf16 v[10:25], v[62:65], v[2:5], 0
	global_load_dwordx4 v[2:5], v[66:67], off offset:128
	v_add_co_u32_e32 v90, vcc, s61, v66
	v_lshlrev_b32_e32 v0, 16, v149
	s_nop 0
	v_addc_co_u32_e32 v91, vcc, 0, v67, vcc
	v_mul_f32_e32 v0, 0xbfb8aa3b, v0
	s_waitcnt vmcnt(3)
	v_mfma_f32_32x32x16_bf16 v[10:25], v[58:61], v[6:9], v[10:25]
	global_load_dwordx4 v[6:9], v[66:67], off offset:160
	v_exp_f32_e32 v0, v0
	s_nop 0
	v_add_f32_e32 v0, 1.0, v0
	v_rcp_f32_e32 v0, v0
	s_waitcnt vmcnt(3)
	v_mfma_f32_32x32x16_bf16 v[10:25], v[54:57], v[26:29], v[10:25]
	global_load_dwordx4 v[26:29], v[66:67], off offset:192
	s_waitcnt vmcnt(3)
	v_mfma_f32_32x32x16_bf16 v[10:25], v[50:53], v[30:33], v[10:25]
	global_load_dwordx4 v[30:33], v[66:67], off offset:224
	s_waitcnt vmcnt(3)
	v_mfma_f32_32x32x16_bf16 v[10:25], v[46:49], v[2:5], v[10:25]
	global_load_dwordx4 v[2:5], v[90:91], off
	global_load_dwordx4 v[70:73], v[90:91], off offset:32
	global_load_dwordx4 v[74:77], v[90:91], off offset:64
	global_load_dwordx4 v[78:81], v[90:91], off offset:96
	global_load_dwordx4 v[82:85], v[90:91], off offset:128
	global_load_dwordx4 v[86:89], v[90:91], off offset:160
	s_waitcnt vmcnt(8)
	v_mfma_f32_32x32x16_bf16 v[10:25], v[42:45], v[6:9], v[10:25]
	v_lshlrev_b32_e32 v6, 16, v150
	v_mul_f32_e32 v6, 0xbfb8aa3b, v6
	v_exp_f32_e32 v6, v6
	v_lshlrev_b32_e32 v7, 16, v151
	v_mul_f32_e32 v7, 0xbfb8aa3b, v7
	v_exp_f32_e32 v7, v7
	v_add_f32_e32 v6, 1.0, v6
	s_waitcnt vmcnt(7)
	v_mfma_f32_32x32x16_bf16 v[10:25], v[38:41], v[26:29], v[10:25]
	global_load_dwordx4 v[26:29], v[90:91], off offset:192
	s_nop 0
	global_load_dwordx4 v[90:93], v[90:91], off offset:224
	v_rcp_f32_e32 v6, v6
	v_lshlrev_b32_e32 v8, 16, v154
	v_mul_f32_e32 v8, 0xbfb8aa3b, v8
	v_exp_f32_e32 v8, v8
	s_waitcnt vmcnt(8)
	v_mfma_f32_32x32x16_bf16 v[10:25], v[34:37], v[30:33], v[10:25]
	v_lshlrev_b32_e32 v32, 16, v158
	v_mul_f32_e32 v32, 0xbfb8aa3b, v32
	v_exp_f32_e32 v32, v32
	s_nop 8
	v_mul_f32_e32 v0, v0, v10
	v_mul_f32_e32 v6, v6, v11
	ds_write2st64_b32 v68, v0, v6 offset1:1
	v_lshlrev_b32_e32 v6, 16, v152
	v_add_f32_e32 v0, 1.0, v7
	v_mul_f32_e32 v6, 0xbfb8aa3b, v6
	v_lshlrev_b32_e32 v7, 16, v153
	v_exp_f32_e32 v6, v6
	v_mul_f32_e32 v7, 0xbfb8aa3b, v7
	v_exp_f32_e32 v7, v7
	v_rcp_f32_e32 v0, v0
	v_add_f32_e32 v6, 1.0, v6
	v_rcp_f32_e32 v6, v6
	v_add_f32_e32 v7, 1.0, v7
	v_rcp_f32_e32 v7, v7
	v_mul_f32_e32 v0, v0, v12
	v_mul_f32_e32 v6, v6, v13
	ds_write2st64_b32 v68, v0, v6 offset0:2 offset1:3
	v_mul_f32_e32 v0, v7, v14
	v_add_f32_e32 v6, 1.0, v8
	v_lshlrev_b32_e32 v7, 16, v155
	v_lshlrev_b32_e32 v8, 16, v156
	v_mul_f32_e32 v7, 0xbfb8aa3b, v7
	v_mul_f32_e32 v8, 0xbfb8aa3b, v8
	v_exp_f32_e32 v7, v7
	v_exp_f32_e32 v8, v8
	v_rcp_f32_e32 v6, v6
	v_add_f32_e32 v7, 1.0, v7
	v_add_f32_e32 v8, 1.0, v8
	v_rcp_f32_e32 v7, v7
	v_rcp_f32_e32 v8, v8
	v_mul_f32_e32 v6, v6, v15
	ds_write2st64_b32 v68, v0, v6 offset0:4 offset1:5
	v_lshlrev_b32_e32 v6, 16, v157
	v_mul_f32_e32 v6, 0xbfb8aa3b, v6
	v_mul_f32_e32 v0, v7, v16
	v_mul_f32_e32 v30, v8, v17
	v_exp_f32_e32 v31, v6
	s_waitcnt vmcnt(7)
	v_mfma_f32_32x32x16_bf16 v[2:17], v[62:65], v[2:5], 0
	ds_write2st64_b32 v68, v0, v30 offset0:6 offset1:7
	v_add_f32_e32 v0, 1.0, v31
	v_add_f32_e32 v30, 1.0, v32
	v_rcp_f32_e32 v0, v0
	v_rcp_f32_e32 v30, v30
	v_lshlrev_b32_e32 v31, 16, v159
	v_mul_f32_e32 v31, 0xbfb8aa3b, v31
	s_waitcnt vmcnt(6)
	v_mfma_f32_32x32x16_bf16 v[2:17], v[58:61], v[70:73], v[2:17]
	v_exp_f32_e32 v31, v31
	v_mul_f32_e32 v0, v0, v18
	v_mul_f32_e32 v18, v30, v19
	ds_write2st64_b32 v68, v0, v18 offset0:8 offset1:9
	v_lshlrev_b32_e32 v18, 16, v160
	v_add_f32_e32 v0, 1.0, v31
	v_mul_f32_e32 v18, 0xbfb8aa3b, v18
	s_waitcnt vmcnt(5)
	v_mfma_f32_32x32x16_bf16 v[2:17], v[54:57], v[74:77], v[2:17]
	v_lshlrev_b32_e32 v19, 16, v161
	v_rcp_f32_e32 v0, v0
	v_exp_f32_e32 v18, v18
	v_mul_f32_e32 v19, 0xbfb8aa3b, v19
	v_exp_f32_e32 v19, v19
	v_mul_f32_e32 v0, v0, v20
	v_add_f32_e32 v18, 1.0, v18
	s_waitcnt vmcnt(4)
	v_mfma_f32_32x32x16_bf16 v[2:17], v[50:53], v[78:81], v[2:17]
	v_lshlrev_b32_e32 v20, 16, v162
	v_rcp_f32_e32 v18, v18
	v_add_f32_e32 v19, 1.0, v19
	v_mul_f32_e32 v20, 0xbfb8aa3b, v20
	v_rcp_f32_e32 v19, v19
	v_exp_f32_e32 v20, v20
	v_mul_f32_e32 v18, v18, v21
	ds_write2st64_b32 v68, v0, v18 offset0:10 offset1:11
	v_mul_f32_e32 v0, v19, v22
	v_add_f32_e32 v18, 1.0, v20
	v_lshlrev_b32_e32 v19, 16, v163
	v_lshlrev_b32_e32 v20, 16, v164
	s_waitcnt vmcnt(3)
	v_mfma_f32_32x32x16_bf16 v[2:17], v[46:49], v[82:85], v[2:17]
	v_mul_f32_e32 v19, 0xbfb8aa3b, v19
	v_mul_f32_e32 v20, 0xbfb8aa3b, v20
	v_exp_f32_e32 v19, v19
	v_exp_f32_e32 v20, v20
	v_rcp_f32_e32 v18, v18
	v_add_co_u32_e32 v22, vcc, s58, v66
	v_add_f32_e32 v19, 1.0, v19
	v_add_f32_e32 v20, 1.0, v20
	v_rcp_f32_e32 v19, v19
	v_rcp_f32_e32 v20, v20
	s_waitcnt vmcnt(2)
	v_mfma_f32_32x32x16_bf16 v[2:17], v[42:45], v[86:89], v[2:17]
	v_mul_f32_e32 v18, v18, v23
	ds_write2st64_b32 v68, v0, v18 offset0:12 offset1:13
	v_mul_f32_e32 v0, v19, v24
	v_mul_f32_e32 v18, v20, v25
	v_addc_co_u32_e32 v23, vcc, 0, v67, vcc
	ds_write2st64_b32 v68, v0, v18 offset0:14 offset1:15
	global_load_dwordx4 v[18:21], v[22:23], off
	global_load_dwordx4 v[70:73], v[22:23], off offset:32
	s_waitcnt vmcnt(3)
; __device__ __forceinline__ float sigm_(float x) { return __builtin_amdgcn_rcpf(1.0f + __builtin_amdgcn_exp2f(-1.4426950408889634f * x)); }
; __device__ __forceinline__ void attn_unit_pp(int b, int h, int qb, int par, const bf16_t* __restrict__ QBp, const bf16_t* __restrict__ KBp, const bf16_t* __restrict__ VBp, ...
;     ...
;     const bf16_t* wpb = WPLp + (size_t)((h >> 1) * 256 + (h & 1) * 128 + r32) * 128 + hi * 8;
; #pragma unroll
;     for (int dp = 0; dp < 2; ++dp) {
;       bf16x8 wp[2][8];
; #pragma unroll
;       for (int e = 0; e < 2; ++e)
; #pragma unroll
;         for (int ks = 0; ks < 8; ++ks) wp[e][ks] = ld8(wpb + (dp * 2 + e) * 32 * 128 + ks * 16);
; #pragma unroll
;       for (int e = 0; e < 2; ++e) { const int d0 = dp * 2 + e; f32x16 acc = f32x16{};
; #pragma unroll
;         for (int ks = 0; ks < 8; ++ks) acc = __builtin_amdgcn_mfma_f32_32x32x16_bf16(pf[ks], wp[e][ks], acc, 0, 0, 0);
; #pragma unroll
;         for (int r = 0; r < 16; ++r) pgs[(d0 * 16 + r) * 64] = sigm_(__uint_as_float(gate16[r * 4 + d0] << 16)) * acc[r]; }
	v_mfma_f32_32x32x16_bf16 v[2:17], v[38:41], v[26:29], v[2:17]
	v_lshlrev_b32_e32 v0, 16, v133
	v_lshlrev_b32_e32 v24, 16, v134
	v_mul_f32_e32 v0, 0xbfb8aa3b, v0
	v_mul_f32_e32 v24, 0xbfb8aa3b, v24
	v_exp_f32_e32 v0, v0
	v_exp_f32_e32 v24, v24
	global_load_dwordx4 v[74:77], v[22:23], off offset:64
	global_load_dwordx4 v[78:81], v[22:23], off offset:96
	s_waitcnt vmcnt(4)
	v_mfma_f32_32x32x16_bf16 v[2:17], v[34:37], v[90:93], v[2:17]
	v_add_f32_e32 v0, 1.0, v0
	v_add_f32_e32 v24, 1.0, v24
	v_rcp_f32_e32 v0, v0
	v_rcp_f32_e32 v24, v24
	v_lshlrev_b32_e32 v25, 16, v136
	v_mul_f32_e32 v25, 0xbfb8aa3b, v25
	v_exp_f32_e32 v25, v25
	s_nop 4
	v_mul_f32_e32 v0, v0, v2
	v_mul_f32_e32 v2, v24, v3
	v_lshlrev_b32_e32 v24, 16, v135
	v_mul_f32_e32 v24, 0xbfb8aa3b, v24
	v_exp_f32_e32 v24, v24
	v_add_f32_e32 v3, 1.0, v25
	v_rcp_f32_e32 v3, v3
	ds_write2st64_b32 v68, v0, v2 offset0:16 offset1:17
	v_add_f32_e32 v2, 1.0, v24
	v_rcp_f32_e32 v2, v2
	v_mul_f32_e32 v0, v3, v4
	v_lshlrev_b32_e32 v3, 16, v138
	v_mul_f32_e32 v3, 0xbfb8aa3b, v3
	v_exp_f32_e32 v24, v3
	v_mul_f32_e32 v25, v2, v5
	global_load_dwordx4 v[2:5], v[22:23], off offset:128
	global_load_dwordx4 v[82:85], v[22:23], off offset:160
	global_load_dwordx4 v[86:89], v[22:23], off offset:192
	global_load_dwordx4 v[90:93], v[22:23], off offset:224
	ds_write2st64_b32 v68, v0, v25 offset0:18 offset1:19
	v_add_f32_e32 v0, 1.0, v24
	v_lshlrev_b32_e32 v24, 16, v137
	v_lshlrev_b32_e32 v25, 16, v140
	v_mul_f32_e32 v24, 0xbfb8aa3b, v24
	v_mul_f32_e32 v25, 0xbfb8aa3b, v25
	v_rcp_f32_e32 v0, v0
	v_exp_f32_e32 v24, v24
	v_exp_f32_e32 v25, v25
	v_mul_f32_e32 v0, v0, v6
	v_add_f32_e32 v6, 1.0, v24
	v_add_f32_e32 v24, 1.0, v25
	v_lshlrev_b32_e32 v25, 16, v139
	v_rcp_f32_e32 v6, v6
	v_mul_f32_e32 v25, 0xbfb8aa3b, v25
	v_rcp_f32_e32 v24, v24
	v_exp_f32_e32 v25, v25
	v_mul_f32_e32 v6, v6, v7
	ds_write2st64_b32 v68, v0, v6 offset0:20 offset1:21
	v_mul_f32_e32 v0, v24, v8
	v_add_f32_e32 v6, 1.0, v25
	s_waitcnt vmcnt(7)
	v_mfma_f32_32x32x16_bf16 v[18:33], v[62:65], v[18:21], 0
	v_lshlrev_b32_e32 v8, 16, v142
	v_lshlrev_b32_e32 v7, 16, v141
	v_mul_f32_e32 v8, 0xbfb8aa3b, v8
	v_rcp_f32_e32 v6, v6
	v_mul_f32_e32 v7, 0xbfb8aa3b, v7
	v_exp_f32_e32 v8, v8
	v_exp_f32_e32 v7, v7
	s_waitcnt vmcnt(6)
	v_mfma_f32_32x32x16_bf16 v[18:33], v[58:61], v[70:73], v[18:33]
	v_mul_f32_e32 v6, v6, v9
	v_add_f32_e32 v8, 1.0, v8
	v_lshlrev_b32_e32 v9, 16, v147
	v_add_f32_e32 v7, 1.0, v7
	v_rcp_f32_e32 v8, v8
	v_mul_f32_e32 v9, 0xbfb8aa3b, v9
	v_rcp_f32_e32 v7, v7
	v_exp_f32_e32 v9, v9
	ds_write2st64_b32 v68, v0, v6 offset0:22 offset1:23
	v_mul_f32_e32 v6, v8, v11
	v_lshlrev_b32_e32 v8, 16, v143
	v_mul_f32_e32 v0, v7, v10
	v_add_f32_e32 v7, 1.0, v9
	v_mul_f32_e32 v8, 0xbfb8aa3b, v8
	v_rcp_f32_e32 v7, v7
	v_exp_f32_e32 v8, v8
	s_waitcnt vmcnt(5)
	v_mfma_f32_32x32x16_bf16 v[18:33], v[54:57], v[74:77], v[18:33]
	ds_write2st64_b32 v68, v0, v6 offset0:24 offset1:25
	v_mul_f32_e32 v0, v7, v12
	v_add_f32_e32 v6, 1.0, v8
	v_lshlrev_b32_e32 v7, 16, v144
	v_mul_f32_e32 v7, 0xbfb8aa3b, v7
	v_rcp_f32_e32 v6, v6
	v_exp_f32_e32 v7, v7
	s_waitcnt vmcnt(4)
	v_mfma_f32_32x32x16_bf16 v[18:33], v[50:53], v[78:81], v[18:33]
	v_lshlrev_b32_e32 v8, 16, v145
	v_mul_f32_e32 v6, v6, v13
	v_add_f32_e32 v7, 1.0, v7
	ds_write2st64_b32 v68, v0, v6 offset0:26 offset1:27
	v_lshlrev_b32_e32 v6, 16, v148
	v_rcp_f32_e32 v7, v7
	v_mul_f32_e32 v6, 0xbfb8aa3b, v6
	v_exp_f32_e32 v9, v6
	v_lshlrev_b32_e32 v6, 16, v146
	v_mul_f32_e32 v6, 0xbfb8aa3b, v6
	v_exp_f32_e32 v10, v6
	v_add_co_u32_e32 v6, vcc, s67, v66
	v_mul_f32_e32 v0, v7, v14
	s_nop 0
	v_addc_co_u32_e32 v7, vcc, 0, v67, vcc
	s_waitcnt vmcnt(3)
	v_mfma_f32_32x32x16_bf16 v[18:33], v[46:49], v[2:5], v[18:33]
	global_load_dwordx4 v[2:5], v[6:7], off
	global_load_dwordx4 v[70:73], v[6:7], off offset:32
	v_mul_f32_e32 v8, 0xbfb8aa3b, v8
	v_exp_f32_e32 v8, v8
	v_add_f32_e32 v9, 1.0, v9
	v_rcp_f32_e32 v9, v9
	v_add_f32_e32 v8, 1.0, v8
	v_rcp_f32_e32 v8, v8
	s_waitcnt vmcnt(4)
	v_mfma_f32_32x32x16_bf16 v[18:33], v[42:45], v[82:85], v[18:33]
	v_mul_f32_e32 v8, v8, v15
	ds_write2st64_b32 v68, v0, v8 offset0:28 offset1:29
	v_add_f32_e32 v0, 1.0, v10
	v_rcp_f32_e32 v0, v0
	v_mul_f32_e32 v8, v9, v16
	s_waitcnt vmcnt(3)
	v_mfma_f32_32x32x16_bf16 v[18:33], v[38:41], v[86:89], v[18:33]
	v_lshlrev_b32_e32 v9, 16, v132
	v_mul_f32_e32 v0, v0, v17
	ds_write2st64_b32 v68, v8, v0 offset0:30 offset1:31
	global_load_dwordx4 v[74:77], v[6:7], off offset:64
	global_load_dwordx4 v[78:81], v[6:7], off offset:96
	global_load_dwordx4 v[82:85], v[6:7], off offset:128
	global_load_dwordx4 v[94:97], v[6:7], off offset:160
	global_load_dwordx4 v[86:89], v[6:7], off offset:192
	global_load_dwordx4 v[134:137], v[6:7], off offset:224
	v_lshlrev_b32_e32 v0, 16, v122
	v_lshlrev_b32_e32 v6, 16, v120
	v_mul_f32_e32 v0, 0xbfb8aa3b, v0
	v_mul_f32_e32 v6, 0xbfb8aa3b, v6
	v_exp_f32_e32 v0, v0
	v_exp_f32_e32 v6, v6
	s_waitcnt vmcnt(8)
; __device__ __forceinline__ float sigm_(float x) { return __builtin_amdgcn_rcpf(1.0f + __builtin_amdgcn_exp2f(-1.4426950408889634f * x)); }
; __device__ __forceinline__ void attn_unit_pp(int b, int h, int qb, int par, const bf16_t* __restrict__ QBp, const bf16_t* __restrict__ KBp, const bf16_t* __restrict__ VBp, ...
;     ...
;     const bf16_t* wpb = WPLp + (size_t)((h >> 1) * 256 + (h & 1) * 128 + r32) * 128 + hi * 8;
; #pragma unroll
;     for (int dp = 0; dp < 2; ++dp) {
;       bf16x8 wp[2][8];
; #pragma unroll
;       for (int e = 0; e < 2; ++e)
; #pragma unroll
;         for (int ks = 0; ks < 8; ++ks) wp[e][ks] = ld8(wpb + (dp * 2 + e) * 32 * 128 + ks * 16);
; #pragma unroll
;       for (int e = 0; e < 2; ++e) { const int d0 = dp * 2 + e; f32x16 acc = f32x16{};
; #pragma unroll
;         for (int ks = 0; ks < 8; ++ks) acc = __builtin_amdgcn_mfma_f32_32x32x16_bf16(pf[ks], wp[e][ks], acc, 0, 0, 0);
; #pragma unroll
;         for (int r = 0; r < 16; ++r) pgs[(d0 * 16 + r) * 64] = sigm_(__uint_as_float(gate16[r * 4 + d0] << 16)) * acc[r]; }
;     }
;     __syncthreads();
	v_mfma_f32_32x32x16_bf16 v[18:33], v[34:37], v[90:93], v[18:33]
	v_lshlrev_b32_e32 v7, 16, v126
	v_add_f32_e32 v0, 1.0, v0
	v_add_f32_e32 v6, 1.0, v6
	v_rcp_f32_e32 v0, v0
	v_rcp_f32_e32 v6, v6
	v_mul_f32_e32 v7, 0xbfb8aa3b, v7
	v_exp_f32_e32 v7, v7
	s_nop 4
	v_mul_f32_e32 v0, v0, v18
	v_mul_f32_e32 v6, v6, v19
	ds_write2st64_b32 v68, v0, v6 offset0:32 offset1:33
	v_lshlrev_b32_e32 v6, 16, v125
	v_add_f32_e32 v0, 1.0, v7
	v_mul_f32_e32 v6, 0xbfb8aa3b, v6
	v_lshlrev_b32_e32 v7, 16, v128
	v_exp_f32_e32 v6, v6
	v_mul_f32_e32 v7, 0xbfb8aa3b, v7
	v_exp_f32_e32 v7, v7
	v_rcp_f32_e32 v0, v0
	v_add_f32_e32 v6, 1.0, v6
	v_rcp_f32_e32 v6, v6
	v_add_f32_e32 v7, 1.0, v7
	v_rcp_f32_e32 v7, v7
	v_lshlrev_b32_e32 v8, 16, v127
	v_mul_f32_e32 v8, 0xbfb8aa3b, v8
	v_mul_f32_e32 v0, v0, v20
	v_exp_f32_e32 v8, v8
	v_mul_f32_e32 v6, v6, v21
	ds_write2st64_b32 v68, v0, v6 offset0:34 offset1:35
	v_mul_f32_e32 v0, v7, v22
	v_lshlrev_b32_e32 v7, 16, v130
	v_mul_f32_e32 v7, 0xbfb8aa3b, v7
	v_exp_f32_e32 v7, v7
	v_add_f32_e32 v6, 1.0, v8
	v_lshlrev_b32_e32 v8, 16, v129
	v_mul_f32_e32 v8, 0xbfb8aa3b, v8
	v_exp_f32_e32 v8, v8
	v_rcp_f32_e32 v6, v6
	v_add_f32_e32 v7, 1.0, v7
	v_mul_f32_e32 v9, 0xbfb8aa3b, v9
	v_rcp_f32_e32 v7, v7
	v_exp_f32_e32 v9, v9
	v_add_f32_e32 v8, 1.0, v8
	v_mul_f32_e32 v6, v6, v23
	v_rcp_f32_e32 v8, v8
	ds_write2st64_b32 v68, v0, v6 offset0:36 offset1:37
	v_mul_f32_e32 v0, v7, v24
	v_add_f32_e32 v7, 1.0, v9
	v_rcp_f32_e32 v7, v7
	v_mul_f32_e32 v6, v8, v25
	v_lshlrev_b32_e32 v8, 16, v131
	v_mul_f32_e32 v8, 0xbfb8aa3b, v8
	v_exp_f32_e32 v18, v8
	ds_write2st64_b32 v68, v0, v6 offset0:38 offset1:39
	v_mul_f32_e32 v0, v7, v26
	s_waitcnt vmcnt(7)
	v_mfma_f32_32x32x16_bf16 v[2:17], v[62:65], v[2:5], 0
	v_add_f32_e32 v18, 1.0, v18
	v_rcp_f32_e32 v18, v18
	v_lshlrev_b32_e32 v19, 16, v118
	v_mul_f32_e32 v19, 0xbfb8aa3b, v19
	v_exp_f32_e32 v19, v19
	v_mul_f32_e32 v18, v18, v27
	ds_write2st64_b32 v68, v0, v18 offset0:40 offset1:41
	s_waitcnt vmcnt(6)
	v_mfma_f32_32x32x16_bf16 v[2:17], v[58:61], v[70:73], v[2:17]
	v_lshlrev_b32_e32 v18, 16, v117
	v_add_f32_e32 v0, 1.0, v19
	v_mul_f32_e32 v18, 0xbfb8aa3b, v18
	v_lshlrev_b32_e32 v19, 16, v121
	v_exp_f32_e32 v18, v18
	v_mul_f32_e32 v19, 0xbfb8aa3b, v19
	v_exp_f32_e32 v19, v19
	s_waitcnt vmcnt(5)
	v_mfma_f32_32x32x16_bf16 v[2:17], v[54:57], v[74:77], v[2:17]
	v_add_f32_e32 v18, 1.0, v18
	v_lshlrev_b32_e32 v20, 16, v119
	v_rcp_f32_e32 v0, v0
	v_rcp_f32_e32 v18, v18
	v_add_f32_e32 v19, 1.0, v19
	v_mul_f32_e32 v20, 0xbfb8aa3b, v20
	v_rcp_f32_e32 v19, v19
	s_waitcnt vmcnt(4)
	v_mfma_f32_32x32x16_bf16 v[2:17], v[50:53], v[78:81], v[2:17]
	v_exp_f32_e32 v20, v20
	v_mul_f32_e32 v0, v0, v28
	v_mul_f32_e32 v18, v18, v29
	ds_write2st64_b32 v68, v0, v18 offset0:42 offset1:43
	v_mul_f32_e32 v0, v19, v30
	v_add_f32_e32 v18, 1.0, v20
	v_lshlrev_b32_e32 v19, 16, v123
	s_waitcnt vmcnt(3)
	v_mfma_f32_32x32x16_bf16 v[2:17], v[46:49], v[82:85], v[2:17]
	v_lshlrev_b32_e32 v20, 16, v124
	v_mul_f32_e32 v19, 0xbfb8aa3b, v19
	v_mul_f32_e32 v20, 0xbfb8aa3b, v20
	v_exp_f32_e32 v19, v19
	v_exp_f32_e32 v20, v20
	v_rcp_f32_e32 v18, v18
	v_add_f32_e32 v19, 1.0, v19
	s_waitcnt vmcnt(2)
	v_mfma_f32_32x32x16_bf16 v[2:17], v[42:45], v[94:97], v[2:17]
	v_add_f32_e32 v20, 1.0, v20
	v_rcp_f32_e32 v19, v19
	v_rcp_f32_e32 v20, v20
	v_mul_f32_e32 v18, v18, v31
	ds_write2st64_b32 v68, v0, v18 offset0:44 offset1:45
	v_mul_f32_e32 v0, v19, v32
	v_mul_f32_e32 v18, v20, v33
	s_waitcnt vmcnt(1)
	v_mfma_f32_32x32x16_bf16 v[2:17], v[38:41], v[86:89], v[2:17]
	ds_write2st64_b32 v68, v0, v18 offset0:46 offset1:47
	v_lshlrev_b32_e32 v0, 16, v102
	v_lshlrev_b32_e32 v18, 16, v101
	v_mul_f32_e32 v0, 0xbfb8aa3b, v0
	v_mul_f32_e32 v18, 0xbfb8aa3b, v18
	v_exp_f32_e32 v0, v0
	v_exp_f32_e32 v18, v18
	s_waitcnt vmcnt(0)
	v_mfma_f32_32x32x16_bf16 v[2:17], v[34:37], v[134:137], v[2:17]
	v_lshlrev_b32_e32 v19, 16, v104
	v_add_f32_e32 v0, 1.0, v0
	v_add_f32_e32 v18, 1.0, v18
	v_rcp_f32_e32 v0, v0
	v_rcp_f32_e32 v18, v18
	v_mul_f32_e32 v19, 0xbfb8aa3b, v19
	v_exp_f32_e32 v19, v19
	s_nop 4
	v_mul_f32_e32 v0, v0, v2
	v_mul_f32_e32 v2, v18, v3
	ds_write2st64_b32 v68, v0, v2 offset0:48 offset1:49
	v_lshlrev_b32_e32 v2, 16, v103
	v_add_f32_e32 v0, 1.0, v19
	v_mul_f32_e32 v2, 0xbfb8aa3b, v2
	v_lshlrev_b32_e32 v3, 16, v106
	v_rcp_f32_e32 v0, v0
	v_exp_f32_e32 v2, v2
	v_mul_f32_e32 v3, 0xbfb8aa3b, v3
	v_exp_f32_e32 v3, v3
	v_mul_f32_e32 v0, v0, v4
	v_add_f32_e32 v2, 1.0, v2
	v_lshlrev_b32_e32 v4, 16, v105
	v_rcp_f32_e32 v2, v2
	v_add_f32_e32 v3, 1.0, v3
	v_mul_f32_e32 v4, 0xbfb8aa3b, v4
	v_rcp_f32_e32 v3, v3
	v_exp_f32_e32 v4, v4
	v_mul_f32_e32 v2, v2, v5
	ds_write2st64_b32 v68, v0, v2 offset0:50 offset1:51
	v_mul_f32_e32 v0, v3, v6
	v_add_f32_e32 v2, 1.0, v4
	v_lshlrev_b32_e32 v3, 16, v108
	v_lshlrev_b32_e32 v4, 16, v107
	v_mul_f32_e32 v3, 0xbfb8aa3b, v3
	v_mul_f32_e32 v4, 0xbfb8aa3b, v4
	v_exp_f32_e32 v3, v3
	v_exp_f32_e32 v4, v4
	v_rcp_f32_e32 v2, v2
	v_add_f32_e32 v3, 1.0, v3
	v_add_f32_e32 v4, 1.0, v4
	v_rcp_f32_e32 v3, v3
	v_rcp_f32_e32 v4, v4
	v_mul_f32_e32 v2, v2, v7
	ds_write2st64_b32 v68, v0, v2 offset0:52 offset1:53
	v_mul_f32_e32 v0, v3, v8
	v_mul_f32_e32 v2, v4, v9
	v_lshlrev_b32_e32 v3, 16, v110
	v_lshlrev_b32_e32 v4, 16, v109
	v_mul_f32_e32 v3, 0xbfb8aa3b, v3
	v_mul_f32_e32 v4, 0xbfb8aa3b, v4
	v_exp_f32_e32 v3, v3
	v_exp_f32_e32 v4, v4
	ds_write2st64_b32 v68, v0, v2 offset0:54 offset1:55
	v_add_f32_e32 v0, 1.0, v3
	v_add_f32_e32 v2, 1.0, v4
	v_rcp_f32_e32 v0, v0
	v_rcp_f32_e32 v2, v2
	v_lshlrev_b32_e32 v3, 16, v112
	v_mul_f32_e32 v3, 0xbfb8aa3b, v3
	v_exp_f32_e32 v3, v3
	v_mul_f32_e32 v0, v0, v10
	v_mul_f32_e32 v2, v2, v11
	ds_write2st64_b32 v68, v0, v2 offset0:56 offset1:57
	v_lshlrev_b32_e32 v2, 16, v111
	v_add_f32_e32 v0, 1.0, v3
	v_mul_f32_e32 v2, 0xbfb8aa3b, v2
	v_lshlrev_b32_e32 v3, 16, v114
	v_exp_f32_e32 v2, v2
	v_mul_f32_e32 v3, 0xbfb8aa3b, v3
	v_exp_f32_e32 v3, v3
	v_lshlrev_b32_e32 v4, 16, v113
	v_add_f32_e32 v2, 1.0, v2
	v_rcp_f32_e32 v0, v0
	v_rcp_f32_e32 v2, v2
	v_add_f32_e32 v3, 1.0, v3
	v_mul_f32_e32 v4, 0xbfb8aa3b, v4
	v_rcp_f32_e32 v3, v3
	v_exp_f32_e32 v4, v4
	v_mul_f32_e32 v0, v0, v12
	v_mul_f32_e32 v2, v2, v13
	ds_write2st64_b32 v68, v0, v2 offset0:58 offset1:59
	v_mul_f32_e32 v0, v3, v14
	v_add_f32_e32 v2, 1.0, v4
	v_lshlrev_b32_e32 v3, 16, v116
	v_lshlrev_b32_e32 v4, 16, v115
	v_mul_f32_e32 v3, 0xbfb8aa3b, v3
	v_mul_f32_e32 v4, 0xbfb8aa3b, v4
	v_exp_f32_e32 v3, v3
	v_exp_f32_e32 v4, v4
	v_rcp_f32_e32 v2, v2
	v_add_f32_e32 v3, 1.0, v3
	v_add_f32_e32 v4, 1.0, v4
	v_rcp_f32_e32 v3, v3
	v_rcp_f32_e32 v4, v4
	v_mul_f32_e32 v2, v2, v15
	ds_write2st64_b32 v68, v0, v2 offset0:60 offset1:61
	v_mul_f32_e32 v0, v3, v16
	v_mul_f32_e32 v2, v4, v17
	ds_write2st64_b32 v68, v0, v2 offset0:62 offset1:63
	s_waitcnt lgkmcnt(0)
	s_barrier
	s_branch .LBB0_338
